# scan2 chain: overlap A/B loads + pipelined LDS reads in f32 MFMA loop; scan chunk: wave0 skips dead accumulator zeroing; v_sub pairs to v_pk_add; scan3 prep: merge four masked bonus-partial blocks int
# speedup vs baseline: 1.0650x; 1.0093x over previous
; #define LAS __attribute__((address_space(3)))
; __device__ __forceinline__ unsigned pk2(float lo, float hi) { const f32v2_t v = {lo, hi}; const bf16v2_t b = __builtin_convertvector(v, bf16v2_t); return __builtin_bit_cast(unsigned, b); }
; __device__ __forceinline__ float fast_sigmoid(float x) { return __builtin_amdgcn_rcpf(1.f + __expf(-x)); }
; __device__ __forceinline__ f32x4 ts4_apply(const RawQ& q, const LAS float* MU, int grp, int col) {
;     const f32x4 pc = {bf2f(q.c.x & 0xffffu), bf2f(q.c.x >> 16), bf2f(q.c.y & 0xffffu), bf2f(q.c.y >> 16)};
;     const f32x4 pp = {bf2f(q.p.x & 0xffffu), bf2f(q.p.x >> 16), bf2f(q.p.y & 0xffffu), bf2f(q.p.y >> 16)};
;     const f32x4 pn = {bf2f(q.n.x & 0xffffu), bf2f(q.n.x >> 16), bf2f(q.n.y & 0xffffu), bf2f(q.n.y >> 16)};
;     const f32x4 m0 = *(const LAS f32x4*)(MU + (grp * 2) * 64 + col), m1 = *(const LAS f32x4*)(MU + (grp * 2 + 1) * 64 + col);
;     return pc + m0 * (pp - pc) + m1 * (pn - pc);
; template <int NV, bool FULL> __device__ __forceinline__ void scan_prep(const ScanLds& L, Raw& R, const bf16* P, const float* mu, int s0, int len, int pos0_next, bool has_next, int h, int dir, const ScanCh& ch, bool doG, int tid_, int wave, int lane_) {
;     ...
;         if (FULL) *(LAS f32x4*)(L.Rs + t * 64 + cq) = ts4_apply(R.q[0], MU, 0, cq);
;         *(LAS f32x4*)(L.KRs + t * 64 + cq) = ts4_apply(R.q[1], MU, 1, cq);
;         *(LAS f32x4*)(L.Vs + t * 64 + cq) = ts4_apply(R.q[2], MU, 2, cq);
;         const f32x4 dw = ts4_apply(R.q[3], MU, 3, cq), da = ts4_apply(R.q[4], MU, 4, cq);
;         v2u w; w.x = pk2(fast_tanh(dw.x), fast_tanh(dw.y)); w.y = pk2(fast_tanh(dw.z), fast_tanh(dw.w)); *(LAS v2u*)(L.DWb + t * 72 + cq) = w;
;         v2u x; x.x = pk2(da.x, da.y); x.y = pk2(da.z, da.w); *(LAS v2u*)(L.DAb + t * 72 + cq) = x;
;         if (doG) { const int c8 = (tid & 15) * 8; const f32x4 g0 = ts4_apply(R.g[0], MU, 5 + (c8 >> 6), c8 & 63), g1 = ts4_apply(R.g[1], MU, 5 + (c8 >> 6), (c8 & 63) + 4);
;             v4u gq; gq.x = pk2(fast_sigmoid(g0.x), fast_sigmoid(g0.y)); gq.y = pk2(fast_sigmoid(g0.z), fast_sigmoid(g0.w)); gq.z = pk2(fast_sigmoid(g1.x), fast_sigmoid(g1.y)); gq.w = pk2(fast_sigmoid(g1.z), fast_sigmoid(g1.w));
;             *(LAS v4u*)(L.DGb + t * 136 + c8) = gq; }
;         if (has_next) raw_load<FULL>(R, P, s0, len, pos0_next, h, dir, doG, tid);
.LBB0_284:
	v_mov_b32_e32 v18, v82
	v_mov_b32_e32 v24, v89
	s_waitcnt lgkmcnt(0)
	v_ashrrev_i32_e32 v1, 4, v18
	v_lshlrev_b32_e32 v18, 2, v18
	v_and_b32_e32 v25, 60, v18
	v_lshl_add_u32 v40, v25, 2, 0
	v_add_u32_e32 v18, 0x24200, v40
	v_add_u32_e32 v26, 0x24300, v40
	s_barrier
	ds_read_b128 v[18:21], v18
	ds_read_b128 v[26:29], v26
	s_waitcnt vmcnt(3)
	v_lshlrev_b32_e32 v22, 16, v98
	v_and_b32_e32 v23, 0xffff0000, v98
	v_lshlrev_b32_e32 v30, 16, v99
	v_and_b32_e32 v31, 0xffff0000, v99
	v_lshlrev_b32_e32 v32, 16, v100
	v_and_b32_e32 v33, 0xffff0000, v100
	v_lshlrev_b32_e32 v34, 16, v101
	v_and_b32_e32 v35, 0xffff0000, v101
	v_lshlrev_b32_e32 v36, 16, v102
	v_and_b32_e32 v37, 0xffff0000, v102
	v_lshlrev_b32_e32 v38, 16, v103
	v_and_b32_e32 v39, 0xffff0000, v103
	v_pk_add_f32 v[32:33], v[32:33], v[22:23] neg_lo:[0,1] neg_hi:[0,1]
	v_pk_add_f32 v[34:35], v[34:35], v[30:31] neg_lo:[0,1] neg_hi:[0,1]
	s_waitcnt lgkmcnt(1)
	v_pk_fma_f32 v[20:21], v[34:35], v[20:21], v[30:31]
	v_pk_fma_f32 v[18:19], v[32:33], v[18:19], v[22:23]
	v_pk_add_f32 v[30:31], v[38:39], v[30:31] neg_lo:[0,1] neg_hi:[0,1]
	v_pk_add_f32 v[22:23], v[36:37], v[22:23] neg_lo:[0,1] neg_hi:[0,1]
	s_waitcnt lgkmcnt(0)
	v_pk_fma_f32 v[18:19], v[22:23], v[26:27], v[18:19]
	v_pk_fma_f32 v[20:21], v[30:31], v[28:29], v[20:21]
	v_lshl_add_u32 v36, v1, 8, v40
	ds_write_b128 v36, v[18:21] offset:45056
	v_add_u32_e32 v18, 0x24400, v40
	v_add_u32_e32 v26, 0x24500, v40
	ds_read_b128 v[18:21], v18
	ds_read_b128 v[26:29], v26
	s_waitcnt vmcnt(2)
	v_lshlrev_b32_e32 v22, 16, v104
	v_and_b32_e32 v23, 0xffff0000, v104
	v_lshlrev_b32_e32 v30, 16, v105
	v_and_b32_e32 v31, 0xffff0000, v105
	v_lshlrev_b32_e32 v32, 16, v106
	v_and_b32_e32 v33, 0xffff0000, v106
	v_lshlrev_b32_e32 v34, 16, v107
	v_and_b32_e32 v35, 0xffff0000, v107
	v_lshlrev_b32_e32 v37, 16, v108
	v_and_b32_e32 v38, 0xffff0000, v108
	v_lshlrev_b32_e32 v39, 16, v109
	v_and_b32_e32 v41, 0xffff0000, v109
	v_pk_add_f32 v[32:33], v[32:33], v[22:23] neg_lo:[0,1] neg_hi:[0,1]
	v_pk_add_f32 v[34:35], v[34:35], v[30:31] neg_lo:[0,1] neg_hi:[0,1]
	s_waitcnt lgkmcnt(1)
	v_pk_fma_f32 v[20:21], v[34:35], v[20:21], v[30:31]
	v_pk_fma_f32 v[18:19], v[32:33], v[18:19], v[22:23]
	v_sub_f32_e32 v31, v41, v31
	v_sub_f32_e32 v30, v39, v30
	v_sub_f32_e32 v23, v38, v23
	v_sub_f32_e32 v22, v37, v22
	s_waitcnt lgkmcnt(0)
	v_pk_fma_f32 v[18:19], v[22:23], v[26:27], v[18:19]
	v_pk_fma_f32 v[20:21], v[30:31], v[28:29], v[20:21]
	ds_write_b128 v36, v[18:21] offset:53248
	v_add_u32_e32 v18, 0x24600, v40
	v_add_u32_e32 v26, 0x24700, v40
	ds_read_b128 v[18:21], v18
	ds_read_b128 v[26:29], v26
	s_waitcnt vmcnt(1)
	v_lshlrev_b32_e32 v22, 16, v110
	v_and_b32_e32 v23, 0xffff0000, v110
	v_lshlrev_b32_e32 v34, 16, v112
	v_and_b32_e32 v35, 0xffff0000, v112
	v_lshlrev_b32_e32 v30, 16, v111
	v_and_b32_e32 v31, 0xffff0000, v111
	v_lshlrev_b32_e32 v32, 16, v113
	v_and_b32_e32 v33, 0xffff0000, v113
	v_lshlrev_b32_e32 v36, 16, v114
	v_and_b32_e32 v37, 0xffff0000, v114
	v_pk_add_f32 v[34:35], v[34:35], v[22:23] neg_lo:[0,1] neg_hi:[0,1]
	v_lshlrev_b32_e32 v38, 16, v115
	v_and_b32_e32 v39, 0xffff0000, v115
	v_pk_add_f32 v[32:33], v[32:33], v[30:31] neg_lo:[0,1] neg_hi:[0,1]
	s_waitcnt lgkmcnt(1)
	v_pk_fma_f32 v[18:19], v[34:35], v[18:19], v[22:23]
	v_pk_add_f32 v[22:23], v[36:37], v[22:23] neg_lo:[0,1] neg_hi:[0,1]
	v_pk_fma_f32 v[20:21], v[32:33], v[20:21], v[30:31]
	v_pk_add_f32 v[30:31], v[38:39], v[30:31] neg_lo:[0,1] neg_hi:[0,1]
	s_waitcnt lgkmcnt(0)
	v_pk_fma_f32 v[22:23], v[22:23], v[26:27], v[18:19]
	v_add_u32_e32 v18, 0x24800, v40
	v_add_u32_e32 v26, 0x24900, v40
	v_pk_fma_f32 v[30:31], v[30:31], v[28:29], v[20:21]
	ds_read_b128 v[18:21], v18
	ds_read_b128 v[26:29], v26
	s_waitcnt vmcnt(0)
	v_lshlrev_b32_e32 v34, 16, v117
	v_and_b32_e32 v35, 0xffff0000, v117
	v_lshlrev_b32_e32 v36, 16, v119
	v_and_b32_e32 v37, 0xffff0000, v119
	v_lshlrev_b32_e32 v43, 16, v121
	v_and_b32_e32 v44, 0xffff0000, v121
	v_pk_add_f32 v[36:37], v[36:37], v[34:35] neg_lo:[0,1] neg_hi:[0,1]
	s_waitcnt lgkmcnt(1)
	v_pk_fma_f32 v[20:21], v[36:37], v[20:21], v[34:35]
	v_sub_f32_e32 v35, v44, v35
	v_sub_f32_e32 v34, v43, v34
	v_add_f32_e32 v22, v22, v22
	v_add_f32_e32 v23, v23, v23
	s_waitcnt lgkmcnt(0)
	v_pk_fma_f32 v[20:21], v[34:35], v[28:29], v[20:21]
	v_add_f32_e32 v28, v30, v30
	v_add_f32_e32 v29, v31, v31
	v_mul_f32_e32 v22, 0x3fb8aa3b, v22
	v_mul_f32_e32 v23, 0x3fb8aa3b, v23
	v_mul_f32_e32 v28, 0x3fb8aa3b, v28
	v_mul_f32_e32 v29, 0x3fb8aa3b, v29
	v_exp_f32_e32 v22, v22
	v_exp_f32_e32 v23, v23
	v_exp_f32_e32 v28, v28
	v_exp_f32_e32 v29, v29
	v_add_f32_e32 v22, 1.0, v22
	v_add_f32_e32 v23, 1.0, v23
	v_add_f32_e32 v28, 1.0, v28
	v_add_f32_e32 v29, 1.0, v29
	v_rcp_f32_e32 v22, v22
	v_rcp_f32_e32 v23, v23
	v_rcp_f32_e32 v28, v28
	v_rcp_f32_e32 v29, v29
	v_lshlrev_b32_e32 v32, 16, v116
	v_and_b32_e32 v33, 0xffff0000, v116
	v_lshlrev_b32_e32 v38, 16, v118
	v_and_b32_e32 v39, 0xffff0000, v118
	v_lshlrev_b32_e32 v41, 16, v120
	v_and_b32_e32 v42, 0xffff0000, v120
	v_pk_add_f32 v[38:39], v[38:39], v[32:33] neg_lo:[0,1] neg_hi:[0,1]
	v_pk_fma_f32 v[18:19], v[38:39], v[18:19], v[32:33]
	v_sub_f32_e32 v33, v42, v33
	v_sub_f32_e32 v32, v41, v32
	v_pk_fma_f32 v[18:19], v[32:33], v[26:27], v[18:19]
	v_pk_fma_f32 v[22:23], v[22:23], 2.0, 1.0 op_sel_hi:[1,0,0] neg_lo:[1,0,0] neg_hi:[1,0,0]
	v_pk_fma_f32 v[26:27], v[28:29], 2.0, 1.0 op_sel_hi:[1,0,0] neg_lo:[1,0,0] neg_hi:[1,0,0]
	v_cvt_pk_bf16_f32 v22, v22, v23
	v_cvt_pk_bf16_f32 v23, v26, v27
	v_mul_lo_u32 v26, v1, s77
	v_lshlrev_b32_e32 v27, 1, v25
	s_cmpk_eq_i32 s13, 0x1e0
	v_add3_u32 v28, s87, v26, v27
	v_cvt_pk_bf16_f32 v18, v18, v19
	v_cvt_pk_bf16_f32 v19, v20, v21
	v_add3_u32 v20, s78, v26, v27
	ds_write_b64 v28, v[22:23]
	ds_write_b64 v20, v[18:19]
	s_cbranch_scc1 .LBB0_302
	s_add_i32 s3, s7, s13
	s_and_b64 s[0:1], s[50:51], exec
	v_sub_u32_e32 v18, 31, v1
	s_cselect_b32 s0, s3, s12
	v_cndmask_b32_e64 v1, v18, v1, s[50:51]
	v_add_u32_e32 v1, s0, v1
	v_add_u32_e32 v20, 0x8000, v1
	v_or_b32_e32 v21, s75, v25
	v_mov_b64_e32 v[18:19], s[8:9]
	s_movk_i32 s0, 0x1800
	v_mad_i64_i32 v[18:19], s[0:1], v20, s0, v[18:19]
	v_lshlrev_b32_e32 v20, 1, v21
	v_mov_b32_e32 v21, v0
	v_lshl_add_u64 v[20:21], v[18:19], 0, v[20:21]
	global_load_dwordx2 v[98:99], v[20:21], off offset:3072
	v_mov_b32_e32 v102, v0
	v_mov_b32_e32 v103, v0
	v_cmp_lt_i32_e64 s[52:53], 0, v1
	v_mov_b64_e32 v[100:101], v[102:103]
	s_and_saveexec_b64 s[0:1], s[52:53]
	s_cbranch_execz .LBB0_287
	global_load_dwordx2 v[100:101], v[20:21], off offset:-3072

; __device__ __forceinline__ int mrow(int r, int hi) { return (r & 3) + 8 * (r >> 2) + 4 * hi; }
; template <int NV, bool WITHY> __device__ __forceinline__ void scan_chunk(const ScanLds& L, f32x16& st, bool hasT, int kt, int vt, int wave, int lane_, bf16* ypark = nullptr) {
;     ...
;     if (wave == 0) {
;         __builtin_amdgcn_s_setprio(3);
; #pragma unroll
;         for (int r = 0; r < 16; ++r) { Q[r] = 0.f; QT[r] = 0.f; }
;         mm32<4>(Q, L.Bt, 72, 0, L.Kap, 72, 0, l31, hi);
;         mm32<4>(QT, L.Kap, 72, 0, L.Bt, 72, 0, l31, hi);
; #pragma unroll
;         for (int r = 0; r < 16; ++r) { const int row = mrow(r, hi); Q[r] = row < l31 ? Q[r] : 0.f; QT[r] = l31 < row ? QT[r] : 0.f; W[r] = (row == l31 ? 1.f : 0.f) - QT[r]; }
;         nat_store(L.BQ, Q, l31, hi); nat_store(L.BQT, QT, l31, hi);
.LBB0_316:
	v_mul_u32_u24_e32 v35, 0x90, v166
	v_lshlrev_b32_e32 v169, 1, v1
	v_mul_u32_u24_e32 v170, 0x50, v166
	v_mov_b32_e32 v50, 0
	s_andn2_b64 vcc, exec, s[0:1]
	v_add3_u32 v172, s5, v35, v169
	v_add3_u32 v171, s62, v170, v1
	s_cbranch_vccz .Lw0skip0
	v_mov_b32_e32 v51, 0
	v_mov_b32_e32 v52, 0
	v_mov_b32_e32 v53, 0
	v_mov_b32_e32 v54, 0
	v_mov_b32_e32 v55, 0
	v_mov_b32_e32 v56, 0
	v_mov_b32_e32 v57, 0
	v_mov_b32_e32 v58, 0
	v_mov_b32_e32 v59, 0
	v_mov_b32_e32 v60, 0
	v_mov_b32_e32 v61, 0
	v_mov_b32_e32 v62, 0
	v_mov_b32_e32 v63, 0
	v_mov_b32_e32 v64, 0
	v_mov_b32_e32 v65, 0
	v_mov_b32_e32 v18, 0
	v_mov_b32_e32 v19, 0
	v_mov_b32_e32 v20, 0
	v_mov_b32_e32 v21, 0
	v_mov_b32_e32 v22, 0
	v_mov_b32_e32 v23, 0
	v_mov_b32_e32 v24, 0
	v_mov_b32_e32 v25, 0
	v_mov_b32_e32 v26, 0
	v_mov_b32_e32 v27, 0
	v_mov_b32_e32 v28, 0
	v_mov_b32_e32 v29, 0
	v_mov_b32_e32 v30, 0
	v_mov_b32_e32 v31, 0
	v_mov_b32_e32 v32, 0
	v_mov_b32_e32 v33, 0
	s_branch .LBB0_318
.Lw0skip0:
	s_setprio 3
	v_add3_u32 v42, s57, v35, v169
	ds_read_b128 v[34:37], v42
	ds_read_b128 v[50:53], v42 offset:32
	ds_read_b128 v[38:41], v172
	ds_read_b128 v[54:57], v172 offset:32
	ds_read_b128 v[58:61], v42 offset:64
	ds_read_b128 v[62:65], v172 offset:64
	ds_read_b128 v[66:69], v42 offset:96
	ds_read_b128 v[70:73], v172 offset:96
	s_add_i32 s0, 0, 0x16000
	s_waitcnt lgkmcnt(5)
	v_mfma_f32_32x32x16_bf16 v[18:33], v[34:37], v[38:41], 0
	v_add3_u32 v74, s0, v170, v1
	v_add_u32_e32 v75, v171, v1
	v_add_u32_e32 v76, v74, v1
	v_add3_u32 v77, 0, v170, v1
	v_add_u32_e32 v78, v77, v1
	v_mfma_f32_32x32x16_bf16 v[34:49], v[38:41], v[34:37], 0
	s_waitcnt lgkmcnt(4)
	v_mfma_f32_32x32x16_bf16 v[34:49], v[54:57], v[50:53], v[34:49]
	v_mfma_f32_32x32x16_bf16 v[18:33], v[50:53], v[54:57], v[18:33]
	v_lshlrev_b32_e32 v50, 2, v168
	v_cmp_lt_i32_e64 s[52:53], v166, v50
	v_cmp_lt_i32_e32 vcc, v50, v166
	v_or_b32_e32 v56, 2, v50
	v_or_b32_e32 v55, 3, v50
	s_waitcnt lgkmcnt(2)
	v_mfma_f32_32x32x16_bf16 v[34:49], v[62:65], v[58:61], v[34:49]
	v_mfma_f32_32x32x16_bf16 v[18:33], v[58:61], v[62:65], v[18:33]
	s_waitcnt lgkmcnt(0)
	v_mfma_f32_32x32x16_bf16 v[34:49], v[70:73], v[66:69], v[34:49]
	v_mfma_f32_32x32x16_bf16 v[18:33], v[66:69], v[70:73], v[18:33]
	s_nop 10
	v_cndmask_b32_e64 v52, 0, v34, s[52:53]
	v_cmp_eq_u32_e64 s[52:53], v50, v166
	v_or_b32_e32 v34, 1, v50
	v_cndmask_b32_e64 v54, v35, 0, vcc
	v_cndmask_b32_e32 v51, 0, v18, vcc
	v_cndmask_b32_e64 v18, 0, 1.0, s[52:53]
	v_cmp_lt_i32_e64 s[52:53], v34, v166
	v_cmp_eq_u32_e32 vcc, v34, v166
	v_sub_f32_e32 v18, v18, v52
	v_cndmask_b32_e64 v53, 0, v19, s[52:53]
	v_cndmask_b32_e64 v19, 0, 1.0, vcc
	v_cmp_lt_i32_e32 vcc, v56, v166
	v_cmp_lt_i32_e64 s[52:53], v166, v55
	v_sub_f32_e32 v19, v19, v54
	v_cndmask_b32_e32 v57, 0, v20, vcc
	v_cmp_lt_i32_e32 vcc, v166, v56
	v_cndmask_b32_e64 v35, 0, v37, s[52:53]
	v_cmp_eq_u32_e64 s[52:53], v55, v166
	v_cndmask_b32_e32 v34, 0, v36, vcc
	v_cmp_lt_i32_e32 vcc, v55, v166
	v_add_u32_e32 v55, 9, v50
	s_nop 0
	v_cndmask_b32_e32 v58, 0, v21, vcc
	v_cmp_eq_u32_e32 vcc, v56, v166
	v_add_u32_e32 v56, 8, v50
	v_cndmask_b32_e64 v21, 0, 1.0, s[52:53]
	v_cndmask_b32_e64 v20, 0, 1.0, vcc
	v_cmp_lt_i32_e32 vcc, v56, v166
	v_cmp_lt_i32_e64 s[52:53], v166, v55
	v_pk_add_f32 v[20:21], v[20:21], v[34:35] neg_lo:[0,1] neg_hi:[0,1]
	v_cndmask_b32_e32 v59, 0, v22, vcc
	v_cmp_lt_i32_e32 vcc, v166, v56
	v_cndmask_b32_e64 v37, 0, v39, s[52:53]
	v_cmp_eq_u32_e64 s[52:53], v55, v166
	v_cndmask_b32_e32 v36, 0, v38, vcc
	v_cmp_lt_i32_e32 vcc, v55, v166
	v_add_u32_e32 v55, 11, v50
	s_nop 0
	v_cndmask_b32_e32 v60, 0, v23, vcc
	v_cmp_eq_u32_e32 vcc, v56, v166
	v_add_u32_e32 v56, 10, v50
	v_cndmask_b32_e64 v23, 0, 1.0, s[52:53]
	v_cndmask_b32_e64 v22, 0, 1.0, vcc
	v_cmp_lt_i32_e32 vcc, v56, v166
	v_cmp_lt_i32_e64 s[52:53], v166, v55
	v_pk_add_f32 v[22:23], v[22:23], v[36:37] neg_lo:[0,1] neg_hi:[0,1]
	v_cndmask_b32_e32 v61, 0, v24, vcc
	v_cmp_lt_i32_e32 vcc, v166, v56
	v_cndmask_b32_e64 v39, 0, v41, s[52:53]
	v_cmp_eq_u32_e64 s[52:53], v55, v166
	v_cndmask_b32_e32 v38, 0, v40, vcc
	v_cmp_lt_i32_e32 vcc, v55, v166
	v_add_u32_e32 v55, 17, v50
	s_nop 0
	v_cndmask_b32_e32 v62, 0, v25, vcc
	v_cmp_eq_u32_e32 vcc, v56, v166
	v_add_u32_e32 v56, 16, v50
	v_cndmask_b32_e64 v25, 0, 1.0, s[52:53]
	v_cndmask_b32_e64 v24, 0, 1.0, vcc
	v_cmp_lt_i32_e32 vcc, v56, v166
	v_cmp_lt_i32_e64 s[52:53], v166, v55
	v_pk_add_f32 v[24:25], v[24:25], v[38:39] neg_lo:[0,1] neg_hi:[0,1]
	v_cndmask_b32_e32 v63, 0, v26, vcc
	v_cmp_lt_i32_e32 vcc, v166, v56
	v_cndmask_b32_e64 v41, 0, v43, s[52:53]
	v_cmp_eq_u32_e64 s[52:53], v55, v166
	v_cndmask_b32_e32 v40, 0, v42, vcc
	v_cmp_lt_i32_e32 vcc, v55, v166
	v_add_u32_e32 v55, 19, v50
	s_nop 0
	v_cndmask_b32_e32 v64, 0, v27, vcc
	v_cmp_eq_u32_e32 vcc, v56, v166
	v_add_u32_e32 v56, 18, v50
	v_cndmask_b32_e64 v27, 0, 1.0, s[52:53]
	v_cndmask_b32_e64 v26, 0, 1.0, vcc
	v_cmp_lt_i32_e32 vcc, v56, v166
	v_cmp_lt_i32_e64 s[52:53], v166, v55
	v_pk_add_f32 v[26:27], v[26:27], v[40:41] neg_lo:[0,1] neg_hi:[0,1]
	v_cndmask_b32_e32 v65, 0, v28, vcc
	v_cmp_lt_i32_e32 vcc, v166, v56
	v_cndmask_b32_e64 v43, 0, v45, s[52:53]
	v_cmp_eq_u32_e64 s[52:53], v55, v166
	v_cndmask_b32_e32 v42, 0, v44, vcc
	v_cmp_lt_i32_e32 vcc, v55, v166
	v_add_u32_e32 v55, 25, v50
	s_nop 0
	v_cndmask_b32_e32 v66, 0, v29, vcc
	v_cmp_eq_u32_e32 vcc, v56, v166
	v_add_u32_e32 v56, 24, v50
	v_cndmask_b32_e64 v29, 0, 1.0, s[52:53]
	v_cndmask_b32_e64 v28, 0, 1.0, vcc
	v_cmp_lt_i32_e32 vcc, v56, v166
	v_cmp_lt_i32_e64 s[52:53], v166, v55
	v_pk_add_f32 v[28:29], v[28:29], v[42:43] neg_lo:[0,1] neg_hi:[0,1]
	v_cndmask_b32_e32 v67, 0, v30, vcc
	v_cmp_lt_i32_e32 vcc, v166, v56
; template <int NV, bool WITHY> __device__ __forceinline__ void scan_chunk(const ScanLds& L, f32x16& st, bool hasT, int kt, int vt, int wave, int lane_, bf16* ypark = nullptr) {
;     ...
;         nat_store(L.BQ, Q, l31, hi); nat_store(L.BQT, QT, l31, hi);
;         {   f32x16 Qn, QTn;
; #pragma unroll
;             for (int r = 0; r < 16; ++r) { Qn[r] = 0.f; QTn[r] = 0.f; }
;             mm32<2>(Qn, L.BQT, 40, 0, L.BQ, 40, 0, l31, hi); mm32<2>(QTn, L.BQ, 40, 0, L.BQT, 40, 0, l31, hi); Q = Qn; QT = QTn; }
; #pragma unroll
;         for (int n = 1; n < 3; ++n) {
;             nat_store(L.BQ, Q, l31, hi); nat_store(L.BQT, QT, l31, hi); nat_store(L.BW, W, l31, hi);
;             f32x16 Qn, QTn;
; #pragma unroll
;             for (int r = 0; r < 16; ++r) { Qn[r] = 0.f; QTn[r] = 0.f; }
;             mm32<2>(W, L.BQ, 40, 0, L.BW, 40, 0, l31, hi); mm32<2>(Qn, L.BQT, 40, 0, L.BQ, 40, 0, l31, hi); mm32<2>(QTn, L.BQ, 40, 0, L.BQT, 40, 0, l31, hi); Q = Qn; QT = QTn; }
	v_cndmask_b32_e64 v45, 0, v47, s[52:53]
	v_cmp_eq_u32_e64 s[52:53], v55, v166
	v_cndmask_b32_e32 v44, 0, v46, vcc
	v_cmp_lt_i32_e32 vcc, v55, v166
	v_add_u32_e32 v55, 27, v50
	v_add_u32_e32 v50, 26, v50
	v_cndmask_b32_e32 v68, 0, v31, vcc
	v_cmp_eq_u32_e32 vcc, v56, v166
	v_cndmask_b32_e64 v31, 0, 1.0, s[52:53]
	v_cmp_lt_i32_e64 s[52:53], v166, v55
	v_cndmask_b32_e64 v30, 0, 1.0, vcc
	v_cmp_lt_i32_e32 vcc, v50, v166
	v_cndmask_b32_e64 v47, 0, v49, s[52:53]
	v_cvt_pk_bf16_f32 v49, v57, v58
	v_cndmask_b32_e32 v56, 0, v32, vcc
	v_cmp_lt_i32_e32 vcc, v166, v50
	v_cmp_eq_u32_e64 s[52:53], v55, v166
	v_pk_add_f32 v[30:31], v[30:31], v[44:45] neg_lo:[0,1] neg_hi:[0,1]
	v_cndmask_b32_e32 v46, 0, v48, vcc
	v_cvt_pk_bf16_f32 v48, v51, v53
	v_cmp_lt_i32_e32 vcc, v55, v166
	ds_write_b64 v74, v[48:49]
	v_cvt_pk_bf16_f32 v48, v59, v60
	v_cvt_pk_bf16_f32 v49, v61, v62
	v_cndmask_b32_e32 v69, 0, v33, vcc
	ds_write_b64 v74, v[48:49] offset:16
	v_cvt_pk_bf16_f32 v48, v63, v64
	v_cvt_pk_bf16_f32 v49, v65, v66
	ds_write_b64 v74, v[48:49] offset:32
	v_cvt_pk_bf16_f32 v48, v67, v68
	v_cvt_pk_bf16_f32 v49, v56, v69
	ds_write_b64 v74, v[48:49] offset:48
	v_cvt_pk_bf16_f32 v49, v34, v35
	v_cvt_pk_bf16_f32 v34, v36, v37
	v_cvt_pk_bf16_f32 v35, v38, v39
	ds_write_b64 v171, v[34:35] offset:16
	v_cvt_pk_bf16_f32 v34, v40, v41
	v_cvt_pk_bf16_f32 v35, v42, v43
	v_cvt_pk_bf16_f32 v48, v52, v54
	ds_write_b64 v171, v[34:35] offset:32
	v_cvt_pk_bf16_f32 v34, v44, v45
	v_cvt_pk_bf16_f32 v35, v46, v47
	ds_write_b64 v171, v[48:49]
	ds_write_b64 v171, v[34:35] offset:48
	v_cmp_eq_u32_e32 vcc, v50, v166
	ds_read_b128 v[50:53], v75
	ds_read_b128 v[66:69], v75 offset:32
	ds_read_b128 v[54:57], v76
	ds_read_b128 v[70:73], v76 offset:32
	v_cndmask_b32_e64 v33, 0, 1.0, s[52:53]
	v_cndmask_b32_e64 v32, 0, 1.0, vcc
	v_pk_add_f32 v[32:33], v[32:33], v[46:47] neg_lo:[0,1] neg_hi:[0,1]
	s_waitcnt lgkmcnt(1)
	v_mfma_f32_32x32x16_bf16 v[34:49], v[50:53], v[54:57], 0
	v_mfma_f32_32x32x16_bf16 v[50:65], v[54:57], v[50:53], 0
	s_waitcnt lgkmcnt(0)
	v_mfma_f32_32x32x16_bf16 v[34:49], v[66:69], v[70:73], v[34:49]
	v_mfma_f32_32x32x16_bf16 v[50:65], v[70:73], v[66:69], v[50:65]
	s_nop 10
	v_cvt_pk_bf16_f32 v34, v34, v35
	v_cvt_pk_bf16_f32 v35, v36, v37
	ds_write_b64 v74, v[34:35]
	v_cvt_pk_bf16_f32 v34, v38, v39
	v_cvt_pk_bf16_f32 v35, v40, v41
	ds_write_b64 v74, v[34:35] offset:16
	v_cvt_pk_bf16_f32 v34, v42, v43
	v_cvt_pk_bf16_f32 v35, v44, v45
	ds_write_b64 v74, v[34:35] offset:32
	v_cvt_pk_bf16_f32 v34, v46, v47
	v_cvt_pk_bf16_f32 v35, v48, v49
	ds_write_b64 v74, v[34:35] offset:48
	v_cvt_pk_bf16_f32 v34, v50, v51
	v_cvt_pk_bf16_f32 v35, v52, v53
	ds_write_b64 v171, v[34:35]
	v_cvt_pk_bf16_f32 v34, v54, v55
	v_cvt_pk_bf16_f32 v35, v56, v57
	ds_write_b64 v171, v[34:35] offset:16
	v_cvt_pk_bf16_f32 v34, v58, v59
	v_cvt_pk_bf16_f32 v35, v60, v61
	ds_write_b64 v171, v[34:35] offset:32
	v_cvt_pk_bf16_f32 v34, v62, v63
	v_cvt_pk_bf16_f32 v35, v64, v65
	ds_write_b64 v171, v[34:35] offset:48
	v_cvt_pk_bf16_f32 v34, v18, v19
	v_cvt_pk_bf16_f32 v35, v20, v21
	ds_write_b64 v77, v[34:35] offset:47104
	v_cvt_pk_bf16_f32 v34, v22, v23
	v_cvt_pk_bf16_f32 v35, v24, v25
	ds_write_b64 v77, v[34:35] offset:47120
	v_cvt_pk_bf16_f32 v34, v26, v27
	v_cvt_pk_bf16_f32 v35, v28, v29
	ds_write_b64 v77, v[34:35] offset:47136
	v_cvt_pk_bf16_f32 v34, v30, v31
	v_cvt_pk_bf16_f32 v35, v32, v33
	ds_write_b64 v77, v[34:35] offset:47152
	ds_read_b128 v[34:37], v76
	ds_read_b128 v[66:69], v76 offset:32
	ds_read_b128 v[38:41], v78 offset:47104
	ds_read_b128 v[42:45], v78 offset:47136
	s_waitcnt lgkmcnt(1)
	v_mfma_f32_32x32x16_bf16 v[18:33], v[34:37], v[38:41], v[18:33]
	ds_read_b128 v[38:41], v75
	ds_read_b128 v[70:73], v75 offset:32
	s_waitcnt lgkmcnt(2)
	v_mfma_f32_32x32x16_bf16 v[18:33], v[66:69], v[42:45], v[18:33]
	s_waitcnt lgkmcnt(1)
	v_mfma_f32_32x32x16_bf16 v[50:65], v[38:41], v[34:37], 0
	v_mfma_f32_32x32x16_bf16 v[34:49], v[34:37], v[38:41], 0
	s_waitcnt lgkmcnt(0)
	v_mfma_f32_32x32x16_bf16 v[34:49], v[66:69], v[70:73], v[34:49]
	v_mfma_f32_32x32x16_bf16 v[50:65], v[70:73], v[66:69], v[50:65]
	s_nop 10
	v_cvt_pk_bf16_f32 v34, v34, v35
	v_cvt_pk_bf16_f32 v35, v36, v37
	ds_write_b64 v171, v[34:35]
	v_cvt_pk_bf16_f32 v34, v38, v39
	v_cvt_pk_bf16_f32 v35, v40, v41
	ds_write_b64 v171, v[34:35] offset:16
	v_cvt_pk_bf16_f32 v34, v42, v43
	v_cvt_pk_bf16_f32 v35, v44, v45
	ds_write_b64 v171, v[34:35] offset:32
	v_cvt_pk_bf16_f32 v34, v46, v47
	v_cvt_pk_bf16_f32 v35, v48, v49
	v_cvt_pk_bf16_f32 v50, v50, v51
	v_cvt_pk_bf16_f32 v51, v52, v53
	ds_write_b64 v171, v[34:35] offset:48
	v_cvt_pk_bf16_f32 v34, v18, v19
	v_cvt_pk_bf16_f32 v35, v20, v21
	ds_write_b64 v74, v[50:51]
	v_cvt_pk_bf16_f32 v50, v54, v55
	v_cvt_pk_bf16_f32 v51, v56, v57
	ds_write_b64 v77, v[34:35] offset:47104
	v_cvt_pk_bf16_f32 v34, v22, v23
	v_cvt_pk_bf16_f32 v35, v24, v25
	ds_write_b64 v74, v[50:51] offset:16
	v_cvt_pk_bf16_f32 v50, v58, v59
	v_cvt_pk_bf16_f32 v51, v60, v61
	ds_write_b64 v77, v[34:35] offset:47120
	v_cvt_pk_bf16_f32 v34, v26, v27
	v_cvt_pk_bf16_f32 v35, v28, v29
	ds_write_b64 v74, v[50:51] offset:32
	v_cvt_pk_bf16_f32 v50, v62, v63
	v_cvt_pk_bf16_f32 v51, v64, v65
	ds_write_b64 v77, v[34:35] offset:47136
	v_cvt_pk_bf16_f32 v34, v30, v31
	v_cvt_pk_bf16_f32 v35, v32, v33
	ds_write_b64 v74, v[50:51] offset:48
	ds_write_b64 v77, v[34:35] offset:47152
	ds_read_b128 v[34:37], v76
	ds_read_b128 v[66:69], v76 offset:32
	ds_read_b128 v[38:41], v78 offset:47104
	ds_read_b128 v[42:45], v78 offset:47136
	s_waitcnt lgkmcnt(1)
	v_mfma_f32_32x32x16_bf16 v[18:33], v[34:37], v[38:41], v[18:33]
	ds_read_b128 v[38:41], v75
	ds_read_b128 v[70:73], v75 offset:32
	s_waitcnt lgkmcnt(2)
	v_mfma_f32_32x32x16_bf16 v[18:33], v[66:69], v[42:45], v[18:33]
	s_waitcnt lgkmcnt(1)
	v_mfma_f32_32x32x16_bf16 v[50:65], v[38:41], v[34:37], 0
	v_mfma_f32_32x32x16_bf16 v[34:49], v[34:37], v[38:41], 0
	s_waitcnt lgkmcnt(0)
	v_mfma_f32_32x32x16_bf16 v[50:65], v[70:73], v[66:69], v[50:65]
	v_mfma_f32_32x32x16_bf16 v[34:49], v[66:69], v[70:73], v[34:49]

; #define LAS __attribute__((address_space(3)))
; __device__ __forceinline__ unsigned pk2(float lo, float hi) { const f32v2_t v = {lo, hi}; const bf16v2_t b = __builtin_convertvector(v, bf16v2_t); return __builtin_bit_cast(unsigned, b); }
; __device__ __forceinline__ float fast_sigmoid(float x) { return __builtin_amdgcn_rcpf(1.f + __expf(-x)); }
; __device__ __forceinline__ f32x4 ts4_apply(const RawQ& q, const LAS float* MU, int grp, int col) {
;     const f32x4 pc = {bf2f(q.c.x & 0xffffu), bf2f(q.c.x >> 16), bf2f(q.c.y & 0xffffu), bf2f(q.c.y >> 16)};
;     const f32x4 pp = {bf2f(q.p.x & 0xffffu), bf2f(q.p.x >> 16), bf2f(q.p.y & 0xffffu), bf2f(q.p.y >> 16)};
;     const f32x4 pn = {bf2f(q.n.x & 0xffffu), bf2f(q.n.x >> 16), bf2f(q.n.y & 0xffffu), bf2f(q.n.y >> 16)};
;     const f32x4 m0 = *(const LAS f32x4*)(MU + (grp * 2) * 64 + col), m1 = *(const LAS f32x4*)(MU + (grp * 2 + 1) * 64 + col);
;     return pc + m0 * (pp - pc) + m1 * (pn - pc);
; template <int NV, bool FULL> __device__ __forceinline__ void scan_prep(const ScanLds& L, Raw& R, const bf16* P, const float* mu, int s0, int len, int pos0_next, bool has_next, int h, int dir, const ScanCh& ch, bool doG, int tid_, int wave, int lane_) {
;     ...
;         if (FULL) *(LAS f32x4*)(L.Rs + t * 64 + cq) = ts4_apply(R.q[0], MU, 0, cq);
;         *(LAS f32x4*)(L.KRs + t * 64 + cq) = ts4_apply(R.q[1], MU, 1, cq);
;         *(LAS f32x4*)(L.Vs + t * 64 + cq) = ts4_apply(R.q[2], MU, 2, cq);
;         const f32x4 dw = ts4_apply(R.q[3], MU, 3, cq), da = ts4_apply(R.q[4], MU, 4, cq);
;         v2u w; w.x = pk2(fast_tanh(dw.x), fast_tanh(dw.y)); w.y = pk2(fast_tanh(dw.z), fast_tanh(dw.w)); *(LAS v2u*)(L.DWb + t * 72 + cq) = w;
;         v2u x; x.x = pk2(da.x, da.y); x.y = pk2(da.z, da.w); *(LAS v2u*)(L.DAb + t * 72 + cq) = x;
;         if (doG) { const int c8 = (tid & 15) * 8; const f32x4 g0 = ts4_apply(R.g[0], MU, 5 + (c8 >> 6), c8 & 63), g1 = ts4_apply(R.g[1], MU, 5 + (c8 >> 6), (c8 & 63) + 4);
;             v4u gq; gq.x = pk2(fast_sigmoid(g0.x), fast_sigmoid(g0.y)); gq.y = pk2(fast_sigmoid(g0.z), fast_sigmoid(g0.w)); gq.z = pk2(fast_sigmoid(g1.x), fast_sigmoid(g1.y)); gq.w = pk2(fast_sigmoid(g1.z), fast_sigmoid(g1.w));
;             *(LAS v4u*)(L.DGb + t * 136 + c8) = gq; }
;         if (has_next) raw_load<FULL>(R, P, s0, len, pos0_next, h, dir, doG, tid);
.LBB0_372:
	v_mov_b32_e32 v18, v82
	v_mov_b32_e32 v24, v89
	s_waitcnt lgkmcnt(0)
	v_ashrrev_i32_e32 v1, 4, v18
	v_lshlrev_b32_e32 v18, 2, v18
	v_and_b32_e32 v25, 60, v18
	v_lshl_add_u32 v40, v25, 2, 0
	v_add_u32_e32 v18, 0x24200, v40
	v_add_u32_e32 v26, 0x24300, v40
	s_barrier
	ds_read_b128 v[18:21], v18
	ds_read_b128 v[26:29], v26
	s_waitcnt vmcnt(3)
	v_lshlrev_b32_e32 v22, 16, v98
	v_and_b32_e32 v23, 0xffff0000, v98
	v_lshlrev_b32_e32 v30, 16, v99
	v_and_b32_e32 v31, 0xffff0000, v99
	v_lshlrev_b32_e32 v32, 16, v100
	v_and_b32_e32 v33, 0xffff0000, v100
	v_lshlrev_b32_e32 v34, 16, v101
	v_and_b32_e32 v35, 0xffff0000, v101
	v_lshlrev_b32_e32 v36, 16, v102
	v_and_b32_e32 v37, 0xffff0000, v102
	v_lshlrev_b32_e32 v38, 16, v103
	v_and_b32_e32 v39, 0xffff0000, v103
	v_pk_add_f32 v[32:33], v[32:33], v[22:23] neg_lo:[0,1] neg_hi:[0,1]
	v_pk_add_f32 v[34:35], v[34:35], v[30:31] neg_lo:[0,1] neg_hi:[0,1]
	s_waitcnt lgkmcnt(1)
	v_pk_fma_f32 v[20:21], v[34:35], v[20:21], v[30:31]
	v_pk_fma_f32 v[18:19], v[32:33], v[18:19], v[22:23]
	v_pk_add_f32 v[30:31], v[38:39], v[30:31] neg_lo:[0,1] neg_hi:[0,1]
	v_pk_add_f32 v[22:23], v[36:37], v[22:23] neg_lo:[0,1] neg_hi:[0,1]
	s_waitcnt lgkmcnt(0)
	v_pk_fma_f32 v[18:19], v[22:23], v[26:27], v[18:19]
	v_pk_fma_f32 v[20:21], v[30:31], v[28:29], v[20:21]
	v_lshl_add_u32 v36, v1, 8, v40
	ds_write_b128 v36, v[18:21] offset:45056
	v_add_u32_e32 v18, 0x24400, v40
	v_add_u32_e32 v26, 0x24500, v40
	ds_read_b128 v[18:21], v18
	ds_read_b128 v[26:29], v26
	s_waitcnt vmcnt(2)
	v_lshlrev_b32_e32 v22, 16, v104
	v_and_b32_e32 v23, 0xffff0000, v104
	v_lshlrev_b32_e32 v30, 16, v105
	v_and_b32_e32 v31, 0xffff0000, v105
	v_lshlrev_b32_e32 v32, 16, v106
	v_and_b32_e32 v33, 0xffff0000, v106
	v_lshlrev_b32_e32 v34, 16, v107
	v_and_b32_e32 v35, 0xffff0000, v107
	v_lshlrev_b32_e32 v37, 16, v108
	v_and_b32_e32 v38, 0xffff0000, v108
	v_lshlrev_b32_e32 v39, 16, v109
	v_and_b32_e32 v41, 0xffff0000, v109
	v_pk_add_f32 v[32:33], v[32:33], v[22:23] neg_lo:[0,1] neg_hi:[0,1]
	v_pk_add_f32 v[34:35], v[34:35], v[30:31] neg_lo:[0,1] neg_hi:[0,1]
	s_waitcnt lgkmcnt(1)
	v_pk_fma_f32 v[20:21], v[34:35], v[20:21], v[30:31]
	v_pk_fma_f32 v[18:19], v[32:33], v[18:19], v[22:23]
	v_sub_f32_e32 v31, v41, v31
	v_sub_f32_e32 v30, v39, v30
	v_sub_f32_e32 v23, v38, v23
	v_sub_f32_e32 v22, v37, v22
	s_waitcnt lgkmcnt(0)
	v_pk_fma_f32 v[18:19], v[22:23], v[26:27], v[18:19]
	v_pk_fma_f32 v[20:21], v[30:31], v[28:29], v[20:21]
	ds_write_b128 v36, v[18:21] offset:53248
	v_add_u32_e32 v18, 0x24600, v40
	v_add_u32_e32 v26, 0x24700, v40
	ds_read_b128 v[18:21], v18
	ds_read_b128 v[26:29], v26
	s_waitcnt vmcnt(1)
	v_lshlrev_b32_e32 v22, 16, v110
	v_and_b32_e32 v23, 0xffff0000, v110
	v_lshlrev_b32_e32 v34, 16, v112
	v_and_b32_e32 v35, 0xffff0000, v112
	v_lshlrev_b32_e32 v30, 16, v111
	v_and_b32_e32 v31, 0xffff0000, v111
	v_lshlrev_b32_e32 v32, 16, v113
	v_and_b32_e32 v33, 0xffff0000, v113
	v_lshlrev_b32_e32 v36, 16, v114
	v_and_b32_e32 v37, 0xffff0000, v114
	v_pk_add_f32 v[34:35], v[34:35], v[22:23] neg_lo:[0,1] neg_hi:[0,1]
	v_lshlrev_b32_e32 v38, 16, v115
	v_and_b32_e32 v39, 0xffff0000, v115
	v_pk_add_f32 v[32:33], v[32:33], v[30:31] neg_lo:[0,1] neg_hi:[0,1]
	s_waitcnt lgkmcnt(1)
	v_pk_fma_f32 v[18:19], v[34:35], v[18:19], v[22:23]
	v_pk_add_f32 v[22:23], v[36:37], v[22:23] neg_lo:[0,1] neg_hi:[0,1]
	v_pk_fma_f32 v[20:21], v[32:33], v[20:21], v[30:31]
	v_pk_add_f32 v[30:31], v[38:39], v[30:31] neg_lo:[0,1] neg_hi:[0,1]
	s_waitcnt lgkmcnt(0)
	v_pk_fma_f32 v[22:23], v[22:23], v[26:27], v[18:19]
	v_add_u32_e32 v18, 0x24800, v40
	v_add_u32_e32 v26, 0x24900, v40
	v_pk_fma_f32 v[30:31], v[30:31], v[28:29], v[20:21]
	ds_read_b128 v[18:21], v18
	ds_read_b128 v[26:29], v26
	s_waitcnt vmcnt(0)
	v_lshlrev_b32_e32 v34, 16, v117
	v_and_b32_e32 v35, 0xffff0000, v117
	v_lshlrev_b32_e32 v36, 16, v119
	v_and_b32_e32 v37, 0xffff0000, v119
	v_lshlrev_b32_e32 v43, 16, v121
	v_and_b32_e32 v44, 0xffff0000, v121
	v_pk_add_f32 v[36:37], v[36:37], v[34:35] neg_lo:[0,1] neg_hi:[0,1]
	s_waitcnt lgkmcnt(1)
	v_pk_fma_f32 v[20:21], v[36:37], v[20:21], v[34:35]
	v_sub_f32_e32 v35, v44, v35
	v_sub_f32_e32 v34, v43, v34
	v_add_f32_e32 v22, v22, v22
	v_add_f32_e32 v23, v23, v23
	s_waitcnt lgkmcnt(0)
	v_pk_fma_f32 v[20:21], v[34:35], v[28:29], v[20:21]
	v_add_f32_e32 v28, v30, v30
	v_add_f32_e32 v29, v31, v31
	v_mul_f32_e32 v22, 0x3fb8aa3b, v22
	v_mul_f32_e32 v23, 0x3fb8aa3b, v23
	v_mul_f32_e32 v28, 0x3fb8aa3b, v28
	v_mul_f32_e32 v29, 0x3fb8aa3b, v29
	v_exp_f32_e32 v22, v22
	v_exp_f32_e32 v23, v23
	v_exp_f32_e32 v28, v28
	v_exp_f32_e32 v29, v29
	v_add_f32_e32 v22, 1.0, v22
	v_add_f32_e32 v23, 1.0, v23
	v_add_f32_e32 v28, 1.0, v28
	v_add_f32_e32 v29, 1.0, v29
	v_rcp_f32_e32 v22, v22
	v_rcp_f32_e32 v23, v23
	v_rcp_f32_e32 v28, v28
	v_rcp_f32_e32 v29, v29
	v_lshlrev_b32_e32 v32, 16, v116
	v_and_b32_e32 v33, 0xffff0000, v116
	v_lshlrev_b32_e32 v38, 16, v118
	v_and_b32_e32 v39, 0xffff0000, v118
	v_lshlrev_b32_e32 v41, 16, v120
	v_and_b32_e32 v42, 0xffff0000, v120
	v_pk_add_f32 v[38:39], v[38:39], v[32:33] neg_lo:[0,1] neg_hi:[0,1]
	v_pk_fma_f32 v[18:19], v[38:39], v[18:19], v[32:33]
	v_sub_f32_e32 v33, v42, v33
	v_sub_f32_e32 v32, v41, v32
	v_pk_fma_f32 v[18:19], v[32:33], v[26:27], v[18:19]
	v_pk_fma_f32 v[22:23], v[22:23], 2.0, 1.0 op_sel_hi:[1,0,0] neg_lo:[1,0,0] neg_hi:[1,0,0]
	v_pk_fma_f32 v[26:27], v[28:29], 2.0, 1.0 op_sel_hi:[1,0,0] neg_lo:[1,0,0] neg_hi:[1,0,0]
	v_cvt_pk_bf16_f32 v22, v22, v23
	v_cvt_pk_bf16_f32 v23, v26, v27
	v_mul_lo_u32 v26, v1, s77
	v_lshlrev_b32_e32 v27, 1, v25
	s_cmpk_eq_i32 s7, 0x400
	v_add3_u32 v28, s87, v26, v27
	v_cvt_pk_bf16_f32 v18, v18, v19
	v_cvt_pk_bf16_f32 v19, v20, v21
	v_add3_u32 v20, s78, v26, v27
	ds_write_b64 v28, v[22:23]
	ds_write_b64 v20, v[18:19]
	s_cbranch_scc1 .LBB0_390
	s_and_b64 s[0:1], s[50:51], exec
	v_sub_u32_e32 v18, 31, v1
	s_cselect_b32 s0, s7, s12
	v_cndmask_b32_e64 v1, v18, v1, s[50:51]
	v_add_u32_e32 v1, s0, v1
	v_add_u32_e32 v20, s3, v1
	v_or_b32_e32 v21, s89, v25
	v_mov_b64_e32 v[18:19], s[8:9]
	s_movk_i32 s0, 0x1800
	v_mad_i64_i32 v[18:19], s[0:1], v20, s0, v[18:19]
	v_lshlrev_b32_e32 v20, 1, v21
	v_mov_b32_e32 v21, v0
	v_lshl_add_u64 v[20:21], v[18:19], 0, v[20:21]
	global_load_dwordx2 v[98:99], v[20:21], off offset:3072
	v_mov_b32_e32 v102, v0
	v_mov_b32_e32 v103, v0
	v_cmp_lt_i32_e64 s[52:53], 0, v1
	v_mov_b64_e32 v[100:101], v[102:103]
	s_and_saveexec_b64 s[0:1], s[52:53]
	s_cbranch_execz .LBB0_375
	global_load_dwordx2 v[100:101], v[20:21], off offset:-3072

; __device__ __forceinline__ int mrow(int r, int hi) { return (r & 3) + 8 * (r >> 2) + 4 * hi; }
; template <int NV, bool WITHY> __device__ __forceinline__ void scan_chunk(const ScanLds& L, f32x16& st, bool hasT, int kt, int vt, int wave, int lane_, bf16* ypark = nullptr) {
;     ...
;     if (wave == 0) {
;         __builtin_amdgcn_s_setprio(3);
; #pragma unroll
;         for (int r = 0; r < 16; ++r) { Q[r] = 0.f; QT[r] = 0.f; }
;         mm32<4>(Q, L.Bt, 72, 0, L.Kap, 72, 0, l31, hi);
;         mm32<4>(QT, L.Kap, 72, 0, L.Bt, 72, 0, l31, hi);
; #pragma unroll
;         for (int r = 0; r < 16; ++r) { const int row = mrow(r, hi); Q[r] = row < l31 ? Q[r] : 0.f; QT[r] = l31 < row ? QT[r] : 0.f; W[r] = (row == l31 ? 1.f : 0.f) - QT[r]; }
;         nat_store(L.BQ, Q, l31, hi); nat_store(L.BQT, QT, l31, hi);
.LBB0_406:
	v_mul_u32_u24_e32 v35, 0x90, v166
	v_lshlrev_b32_e32 v169, 4, v168
	v_mul_u32_u24_e32 v170, 0x50, v166
	v_mov_b32_e32 v50, 0
	s_andn2_b64 vcc, exec, s[0:1]
	v_add3_u32 v174, s5, v35, v169
	v_add3_u32 v172, s21, v170, v1
	v_add3_u32 v173, s20, v170, v1
	v_add3_u32 v171, s34, v170, v1
	s_cbranch_vccz .Lw0skip1
	v_mov_b32_e32 v51, 0
	v_mov_b32_e32 v52, 0
	v_mov_b32_e32 v53, 0
	v_mov_b32_e32 v54, 0
	v_mov_b32_e32 v55, 0
	v_mov_b32_e32 v56, 0
	v_mov_b32_e32 v57, 0
	v_mov_b32_e32 v58, 0
	v_mov_b32_e32 v59, 0
	v_mov_b32_e32 v60, 0
	v_mov_b32_e32 v61, 0
	v_mov_b32_e32 v62, 0
	v_mov_b32_e32 v63, 0
	v_mov_b32_e32 v64, 0
	v_mov_b32_e32 v65, 0
	v_mov_b32_e32 v18, 0
	v_mov_b32_e32 v19, 0
	v_mov_b32_e32 v20, 0
	v_mov_b32_e32 v21, 0
	v_mov_b32_e32 v22, 0
	v_mov_b32_e32 v23, 0
	v_mov_b32_e32 v24, 0
	v_mov_b32_e32 v25, 0
	v_mov_b32_e32 v26, 0
	v_mov_b32_e32 v27, 0
	v_mov_b32_e32 v28, 0
	v_mov_b32_e32 v29, 0
	v_mov_b32_e32 v30, 0
	v_mov_b32_e32 v31, 0
	v_mov_b32_e32 v32, 0
	v_mov_b32_e32 v33, 0
	s_branch .LBB0_408
.Lw0skip1:
	s_setprio 3
	v_add3_u32 v42, s57, v35, v169
	ds_read_b128 v[34:37], v42
	ds_read_b128 v[50:53], v42 offset:32
	ds_read_b128 v[38:41], v174
	ds_read_b128 v[54:57], v174 offset:32
	ds_read_b128 v[58:61], v42 offset:64
	ds_read_b128 v[62:65], v174 offset:64
	ds_read_b128 v[66:69], v42 offset:96
	ds_read_b128 v[70:73], v174 offset:96
	v_add_u32_e32 v74, v173, v1
	s_waitcnt lgkmcnt(5)
	v_mfma_f32_32x32x16_bf16 v[18:33], v[34:37], v[38:41], 0
	v_add_u32_e32 v75, v172, v1
	v_add_u32_e32 v76, v171, v1
	v_mfma_f32_32x32x16_bf16 v[34:49], v[38:41], v[34:37], 0
	s_waitcnt lgkmcnt(4)
	v_mfma_f32_32x32x16_bf16 v[34:49], v[54:57], v[50:53], v[34:49]
	v_mfma_f32_32x32x16_bf16 v[18:33], v[50:53], v[54:57], v[18:33]
	v_lshlrev_b32_e32 v50, 2, v168
	v_cmp_lt_i32_e64 s[54:55], v166, v50
	v_cmp_lt_i32_e32 vcc, v50, v166
	v_or_b32_e32 v56, 2, v50
	v_or_b32_e32 v55, 3, v50
	s_waitcnt lgkmcnt(2)
	v_mfma_f32_32x32x16_bf16 v[34:49], v[62:65], v[58:61], v[34:49]
	v_mfma_f32_32x32x16_bf16 v[18:33], v[58:61], v[62:65], v[18:33]
	s_waitcnt lgkmcnt(0)
	v_mfma_f32_32x32x16_bf16 v[34:49], v[70:73], v[66:69], v[34:49]
	v_mfma_f32_32x32x16_bf16 v[18:33], v[66:69], v[70:73], v[18:33]
	s_nop 10
	v_cndmask_b32_e64 v52, 0, v34, s[54:55]
	v_cmp_eq_u32_e64 s[54:55], v50, v166
	v_or_b32_e32 v34, 1, v50
	v_cndmask_b32_e64 v54, v35, 0, vcc
	v_cndmask_b32_e32 v51, 0, v18, vcc
	v_cndmask_b32_e64 v18, 0, 1.0, s[54:55]
	v_cmp_lt_i32_e64 s[54:55], v34, v166
	v_cmp_eq_u32_e32 vcc, v34, v166
	v_sub_f32_e32 v18, v18, v52
	v_cndmask_b32_e64 v53, 0, v19, s[54:55]
	v_cndmask_b32_e64 v19, 0, 1.0, vcc
	v_cmp_lt_i32_e32 vcc, v56, v166
	v_cmp_lt_i32_e64 s[54:55], v166, v55
	v_sub_f32_e32 v19, v19, v54
	v_cndmask_b32_e32 v57, 0, v20, vcc
	v_cmp_lt_i32_e32 vcc, v166, v56
	v_cndmask_b32_e64 v35, 0, v37, s[54:55]
	v_cmp_eq_u32_e64 s[54:55], v55, v166
	v_cndmask_b32_e32 v34, 0, v36, vcc
	v_cmp_lt_i32_e32 vcc, v55, v166
	v_add_u32_e32 v55, 9, v50
	s_nop 0
	v_cndmask_b32_e32 v58, 0, v21, vcc
	v_cmp_eq_u32_e32 vcc, v56, v166
	v_add_u32_e32 v56, 8, v50
	v_cndmask_b32_e64 v21, 0, 1.0, s[54:55]
	v_cndmask_b32_e64 v20, 0, 1.0, vcc
	v_cmp_lt_i32_e32 vcc, v56, v166
	v_cmp_lt_i32_e64 s[54:55], v166, v55
	v_pk_add_f32 v[20:21], v[20:21], v[34:35] neg_lo:[0,1] neg_hi:[0,1]
	v_cndmask_b32_e32 v59, 0, v22, vcc
	v_cmp_lt_i32_e32 vcc, v166, v56
	v_cndmask_b32_e64 v37, 0, v39, s[54:55]
	v_cmp_eq_u32_e64 s[54:55], v55, v166
	v_cndmask_b32_e32 v36, 0, v38, vcc
	v_cmp_lt_i32_e32 vcc, v55, v166
	v_add_u32_e32 v55, 11, v50
	s_nop 0
	v_cndmask_b32_e32 v60, 0, v23, vcc
	v_cmp_eq_u32_e32 vcc, v56, v166
	v_add_u32_e32 v56, 10, v50
	v_cndmask_b32_e64 v23, 0, 1.0, s[54:55]
	v_cndmask_b32_e64 v22, 0, 1.0, vcc
	v_cmp_lt_i32_e32 vcc, v56, v166
	v_cmp_lt_i32_e64 s[54:55], v166, v55
	v_pk_add_f32 v[22:23], v[22:23], v[36:37] neg_lo:[0,1] neg_hi:[0,1]
	v_cndmask_b32_e32 v61, 0, v24, vcc
	v_cmp_lt_i32_e32 vcc, v166, v56
	v_cndmask_b32_e64 v39, 0, v41, s[54:55]
	v_cmp_eq_u32_e64 s[54:55], v55, v166
	v_cndmask_b32_e32 v38, 0, v40, vcc
	v_cmp_lt_i32_e32 vcc, v55, v166
	v_add_u32_e32 v55, 17, v50
	s_nop 0
	v_cndmask_b32_e32 v62, 0, v25, vcc
	v_cmp_eq_u32_e32 vcc, v56, v166
	v_add_u32_e32 v56, 16, v50
	v_cndmask_b32_e64 v25, 0, 1.0, s[54:55]
	v_cndmask_b32_e64 v24, 0, 1.0, vcc
	v_cmp_lt_i32_e32 vcc, v56, v166
	v_cmp_lt_i32_e64 s[54:55], v166, v55
	v_pk_add_f32 v[24:25], v[24:25], v[38:39] neg_lo:[0,1] neg_hi:[0,1]
	v_cndmask_b32_e32 v63, 0, v26, vcc
	v_cmp_lt_i32_e32 vcc, v166, v56
	v_cndmask_b32_e64 v41, 0, v43, s[54:55]
	v_cmp_eq_u32_e64 s[54:55], v55, v166
	v_cndmask_b32_e32 v40, 0, v42, vcc
	v_cmp_lt_i32_e32 vcc, v55, v166
	v_add_u32_e32 v55, 19, v50
	s_nop 0
	v_cndmask_b32_e32 v64, 0, v27, vcc
	v_cmp_eq_u32_e32 vcc, v56, v166
	v_add_u32_e32 v56, 18, v50
	v_cndmask_b32_e64 v27, 0, 1.0, s[54:55]
	v_cndmask_b32_e64 v26, 0, 1.0, vcc
	v_cmp_lt_i32_e32 vcc, v56, v166
	v_cmp_lt_i32_e64 s[54:55], v166, v55
	v_pk_add_f32 v[26:27], v[26:27], v[40:41] neg_lo:[0,1] neg_hi:[0,1]
	v_cndmask_b32_e32 v65, 0, v28, vcc
	v_cmp_lt_i32_e32 vcc, v166, v56
	v_cndmask_b32_e64 v43, 0, v45, s[54:55]
	v_cmp_eq_u32_e64 s[54:55], v55, v166
	v_cndmask_b32_e32 v42, 0, v44, vcc
	v_cmp_lt_i32_e32 vcc, v55, v166
	v_add_u32_e32 v55, 25, v50
	s_nop 0
	v_cndmask_b32_e32 v66, 0, v29, vcc
	v_cmp_eq_u32_e32 vcc, v56, v166
	v_add_u32_e32 v56, 24, v50
	v_cndmask_b32_e64 v29, 0, 1.0, s[54:55]
	v_cndmask_b32_e64 v28, 0, 1.0, vcc
	v_cmp_lt_i32_e32 vcc, v56, v166
	v_cmp_lt_i32_e64 s[54:55], v166, v55
	v_pk_add_f32 v[28:29], v[28:29], v[42:43] neg_lo:[0,1] neg_hi:[0,1]
	v_cndmask_b32_e32 v67, 0, v30, vcc
	v_cmp_lt_i32_e32 vcc, v166, v56
	v_cndmask_b32_e64 v45, 0, v47, s[54:55]
; template <int NV, bool WITHY> __device__ __forceinline__ void scan_chunk(const ScanLds& L, f32x16& st, bool hasT, int kt, int vt, int wave, int lane_, bf16* ypark = nullptr) {
;     ...
;         nat_store(L.BQ, Q, l31, hi); nat_store(L.BQT, QT, l31, hi);
;         {   f32x16 Qn, QTn;
; #pragma unroll
;             for (int r = 0; r < 16; ++r) { Qn[r] = 0.f; QTn[r] = 0.f; }
;             mm32<2>(Qn, L.BQT, 40, 0, L.BQ, 40, 0, l31, hi); mm32<2>(QTn, L.BQ, 40, 0, L.BQT, 40, 0, l31, hi); Q = Qn; QT = QTn; }
; #pragma unroll
;         for (int n = 1; n < 3; ++n) {
;             nat_store(L.BQ, Q, l31, hi); nat_store(L.BQT, QT, l31, hi); nat_store(L.BW, W, l31, hi);
;             f32x16 Qn, QTn;
; #pragma unroll
;             for (int r = 0; r < 16; ++r) { Qn[r] = 0.f; QTn[r] = 0.f; }
;             mm32<2>(W, L.BQ, 40, 0, L.BW, 40, 0, l31, hi); mm32<2>(Qn, L.BQT, 40, 0, L.BQ, 40, 0, l31, hi); mm32<2>(QTn, L.BQ, 40, 0, L.BQT, 40, 0, l31, hi); Q = Qn; QT = QTn; }
	v_cmp_eq_u32_e64 s[54:55], v55, v166
	v_cndmask_b32_e32 v44, 0, v46, vcc
	v_cmp_lt_i32_e32 vcc, v55, v166
	v_add_u32_e32 v55, 27, v50
	v_add_u32_e32 v50, 26, v50
	v_cndmask_b32_e32 v68, 0, v31, vcc
	v_cmp_eq_u32_e32 vcc, v56, v166
	v_cndmask_b32_e64 v31, 0, 1.0, s[54:55]
	v_cmp_lt_i32_e64 s[54:55], v166, v55
	v_cndmask_b32_e64 v30, 0, 1.0, vcc
	v_cmp_lt_i32_e32 vcc, v50, v166
	v_cndmask_b32_e64 v47, 0, v49, s[54:55]
	v_cvt_pk_bf16_f32 v49, v57, v58
	v_cndmask_b32_e32 v56, 0, v32, vcc
	v_cmp_lt_i32_e32 vcc, v166, v50
	v_cmp_eq_u32_e64 s[54:55], v55, v166
	v_pk_add_f32 v[30:31], v[30:31], v[44:45] neg_lo:[0,1] neg_hi:[0,1]
	v_cndmask_b32_e32 v46, 0, v48, vcc
	v_cvt_pk_bf16_f32 v48, v51, v53
	v_cmp_lt_i32_e32 vcc, v55, v166
	ds_write_b64 v172, v[48:49]
	v_cvt_pk_bf16_f32 v48, v59, v60
	v_cvt_pk_bf16_f32 v49, v61, v62
	v_cndmask_b32_e32 v69, 0, v33, vcc
	ds_write_b64 v172, v[48:49] offset:16
	v_cvt_pk_bf16_f32 v48, v63, v64
	v_cvt_pk_bf16_f32 v49, v65, v66
	ds_write_b64 v172, v[48:49] offset:32
	v_cvt_pk_bf16_f32 v48, v67, v68
	v_cvt_pk_bf16_f32 v49, v56, v69
	ds_write_b64 v172, v[48:49] offset:48
	v_cvt_pk_bf16_f32 v49, v34, v35
	v_cvt_pk_bf16_f32 v34, v36, v37
	v_cvt_pk_bf16_f32 v35, v38, v39
	ds_write_b64 v173, v[34:35] offset:16
	v_cvt_pk_bf16_f32 v34, v40, v41
	v_cvt_pk_bf16_f32 v35, v42, v43
	v_cvt_pk_bf16_f32 v48, v52, v54
	ds_write_b64 v173, v[34:35] offset:32
	v_cvt_pk_bf16_f32 v34, v44, v45
	v_cvt_pk_bf16_f32 v35, v46, v47
	ds_write_b64 v173, v[48:49]
	ds_write_b64 v173, v[34:35] offset:48
	v_cmp_eq_u32_e32 vcc, v50, v166
	ds_read_b128 v[50:53], v74
	ds_read_b128 v[66:69], v74 offset:32
	ds_read_b128 v[54:57], v75
	ds_read_b128 v[70:73], v75 offset:32
	v_cndmask_b32_e64 v33, 0, 1.0, s[54:55]
	v_cndmask_b32_e64 v32, 0, 1.0, vcc
	v_pk_add_f32 v[32:33], v[32:33], v[46:47] neg_lo:[0,1] neg_hi:[0,1]
	s_waitcnt lgkmcnt(1)
	v_mfma_f32_32x32x16_bf16 v[34:49], v[50:53], v[54:57], 0
	v_mfma_f32_32x32x16_bf16 v[50:65], v[54:57], v[50:53], 0
	s_waitcnt lgkmcnt(0)
	v_mfma_f32_32x32x16_bf16 v[34:49], v[66:69], v[70:73], v[34:49]
	v_mfma_f32_32x32x16_bf16 v[50:65], v[70:73], v[66:69], v[50:65]
	s_nop 10
	v_cvt_pk_bf16_f32 v34, v34, v35
	v_cvt_pk_bf16_f32 v35, v36, v37
	ds_write_b64 v172, v[34:35]
	v_cvt_pk_bf16_f32 v34, v38, v39
	v_cvt_pk_bf16_f32 v35, v40, v41
	ds_write_b64 v172, v[34:35] offset:16
	v_cvt_pk_bf16_f32 v34, v42, v43
	v_cvt_pk_bf16_f32 v35, v44, v45
	ds_write_b64 v172, v[34:35] offset:32
	v_cvt_pk_bf16_f32 v34, v46, v47
	v_cvt_pk_bf16_f32 v35, v48, v49
	ds_write_b64 v172, v[34:35] offset:48
	v_cvt_pk_bf16_f32 v34, v50, v51
	v_cvt_pk_bf16_f32 v35, v52, v53
	ds_write_b64 v173, v[34:35]
	v_cvt_pk_bf16_f32 v34, v54, v55
	v_cvt_pk_bf16_f32 v35, v56, v57
	ds_write_b64 v173, v[34:35] offset:16
	v_cvt_pk_bf16_f32 v34, v58, v59
	v_cvt_pk_bf16_f32 v35, v60, v61
	ds_write_b64 v173, v[34:35] offset:32
	v_cvt_pk_bf16_f32 v34, v62, v63
	v_cvt_pk_bf16_f32 v35, v64, v65
	ds_write_b64 v173, v[34:35] offset:48
	v_cvt_pk_bf16_f32 v34, v18, v19
	v_cvt_pk_bf16_f32 v35, v20, v21
	ds_write_b64 v171, v[34:35]
	v_cvt_pk_bf16_f32 v34, v22, v23
	v_cvt_pk_bf16_f32 v35, v24, v25
	ds_write_b64 v171, v[34:35] offset:16
	v_cvt_pk_bf16_f32 v34, v26, v27
	v_cvt_pk_bf16_f32 v35, v28, v29
	ds_write_b64 v171, v[34:35] offset:32
	v_cvt_pk_bf16_f32 v34, v30, v31
	v_cvt_pk_bf16_f32 v35, v32, v33
	ds_write_b64 v171, v[34:35] offset:48
	ds_read_b128 v[34:37], v75
	ds_read_b128 v[66:69], v75 offset:32
	ds_read_b128 v[38:41], v76
	ds_read_b128 v[42:45], v76 offset:32
	s_waitcnt lgkmcnt(1)
	v_mfma_f32_32x32x16_bf16 v[18:33], v[34:37], v[38:41], v[18:33]
	ds_read_b128 v[38:41], v74
	ds_read_b128 v[70:73], v74 offset:32
	s_waitcnt lgkmcnt(2)
	v_mfma_f32_32x32x16_bf16 v[18:33], v[66:69], v[42:45], v[18:33]
	s_waitcnt lgkmcnt(1)
	v_mfma_f32_32x32x16_bf16 v[50:65], v[38:41], v[34:37], 0
	v_mfma_f32_32x32x16_bf16 v[34:49], v[34:37], v[38:41], 0
	s_waitcnt lgkmcnt(0)
	v_mfma_f32_32x32x16_bf16 v[34:49], v[66:69], v[70:73], v[34:49]
	v_mfma_f32_32x32x16_bf16 v[50:65], v[70:73], v[66:69], v[50:65]
	s_nop 10
	v_cvt_pk_bf16_f32 v34, v34, v35
	v_cvt_pk_bf16_f32 v35, v36, v37
	ds_write_b64 v173, v[34:35]
	v_cvt_pk_bf16_f32 v34, v38, v39
	v_cvt_pk_bf16_f32 v35, v40, v41
	ds_write_b64 v173, v[34:35] offset:16
	v_cvt_pk_bf16_f32 v34, v42, v43
	v_cvt_pk_bf16_f32 v35, v44, v45
	ds_write_b64 v173, v[34:35] offset:32
	v_cvt_pk_bf16_f32 v34, v46, v47
	v_cvt_pk_bf16_f32 v35, v48, v49
	v_cvt_pk_bf16_f32 v50, v50, v51
	v_cvt_pk_bf16_f32 v51, v52, v53
	ds_write_b64 v173, v[34:35] offset:48
	v_cvt_pk_bf16_f32 v34, v18, v19
	v_cvt_pk_bf16_f32 v35, v20, v21
	ds_write_b64 v172, v[50:51]
	v_cvt_pk_bf16_f32 v50, v54, v55
	v_cvt_pk_bf16_f32 v51, v56, v57
	ds_write_b64 v171, v[34:35]
	v_cvt_pk_bf16_f32 v34, v22, v23
	v_cvt_pk_bf16_f32 v35, v24, v25
	ds_write_b64 v172, v[50:51] offset:16
	v_cvt_pk_bf16_f32 v50, v58, v59
	v_cvt_pk_bf16_f32 v51, v60, v61
	ds_write_b64 v171, v[34:35] offset:16
	v_cvt_pk_bf16_f32 v34, v26, v27
	v_cvt_pk_bf16_f32 v35, v28, v29
	ds_write_b64 v172, v[50:51] offset:32
	v_cvt_pk_bf16_f32 v50, v62, v63
	v_cvt_pk_bf16_f32 v51, v64, v65
	ds_write_b64 v171, v[34:35] offset:32
	v_cvt_pk_bf16_f32 v34, v30, v31
	v_cvt_pk_bf16_f32 v35, v32, v33
	ds_write_b64 v172, v[50:51] offset:48
	ds_write_b64 v171, v[34:35] offset:48
	ds_read_b128 v[34:37], v75
	ds_read_b128 v[66:69], v75 offset:32
	ds_read_b128 v[38:41], v76
	ds_read_b128 v[42:45], v76 offset:32
	s_waitcnt lgkmcnt(1)
	v_mfma_f32_32x32x16_bf16 v[18:33], v[34:37], v[38:41], v[18:33]
	ds_read_b128 v[38:41], v74
	ds_read_b128 v[70:73], v74 offset:32
	s_waitcnt lgkmcnt(2)
	v_mfma_f32_32x32x16_bf16 v[18:33], v[66:69], v[42:45], v[18:33]
	s_waitcnt lgkmcnt(1)
	v_mfma_f32_32x32x16_bf16 v[50:65], v[38:41], v[34:37], 0
	v_mfma_f32_32x32x16_bf16 v[34:49], v[34:37], v[38:41], 0
	s_waitcnt lgkmcnt(0)
	v_mfma_f32_32x32x16_bf16 v[50:65], v[70:73], v[66:69], v[50:65]
	v_mfma_f32_32x32x16_bf16 v[34:49], v[66:69], v[70:73], v[34:49]

; #define LAS __attribute__((address_space(3)))
; __device__ __forceinline__ int mrow(int r, int hi) { return (r & 3) + 8 * (r >> 2) + 4 * hi; }
; __device__ __forceinline__ void scan_pass2(LAS unsigned char* lds, const Args& a, int id, int tid) {
;     ...
;     for (int s = 0; s < nseg; ++s) {
;         float* AB = (float*)(a.ws + WS_AB) + (size_t)(it0 + s) * 8192;
;         __syncthreads();
;         if (s == nseg - 1) { *(f32x4*)(AB + 4096 + v * 64 + kq) = (f32x4){Sm[v * 65 + kq], Sm[v * 65 + kq + 1], Sm[v * 65 + kq + 2], Sm[v * 65 + kq + 3]};
;                              *(f32x4*)(AB + 4096 + v * 64 + kq + 4) = (f32x4){Sm[v * 65 + kq + 4], Sm[v * 65 + kq + 5], Sm[v * 65 + kq + 6], Sm[v * 65 + kq + 7]}; break; }
;         { const f32x4 a0 = *(const f32x4*)(AB + tid * 8), a1 = *(const f32x4*)(AB + tid * 8 + 4); *(LAS f32x4*)(Am + tid * 8) = a0; *(LAS f32x4*)(Am + tid * 8 + 4) = a1; }
;         f32x16 acc;
;         if (wave < 4) {
; #pragma unroll
;             for (int r = 0; r < 16; ++r) acc[r] = AB[4096 + (32 * vtl + mrow(r, hi)) * 64 + 32 * ktl + l31];
;         }
;         __syncthreads();
;         *(f32x4*)(AB + 4096 + v * 64 + kq) = (f32x4){Sm[v * 65 + kq], Sm[v * 65 + kq + 1], Sm[v * 65 + kq + 2], Sm[v * 65 + kq + 3]};
;         *(f32x4*)(AB + 4096 + v * 64 + kq + 4) = (f32x4){Sm[v * 65 + kq + 4], Sm[v * 65 + kq + 5], Sm[v * 65 + kq + 6], Sm[v * 65 + kq + 7]};
;         if (wave < 4) {
; #pragma unroll 8
;             for (int ks = 0; ks < 32; ++ks) acc = __builtin_amdgcn_mfma_f32_32x32x2f32(Sm[(32 * vtl + l31) * 65 + 2 * ks + hi], Am[(2 * ks + hi) * 64 + 32 * ktl + l31], acc, 0, 0, 0);
;         }
.LBB0_487:
	s_add_i32 s0, s17, s13
	s_ashr_i32 s1, s0, 31
	s_lshl_b64 s[0:1], s[0:1], 15
	s_add_u32 s2, s8, s0
	s_addc_u32 s3, s9, s1
	s_cmp_eq_u32 s17, 31
	s_cselect_b64 s[0:1], -1, 0
	s_cmp_lg_u32 s17, 31
	s_mov_b64 s[6:7], -1
	s_waitcnt lgkmcnt(0)
	s_barrier
	s_cbranch_scc0 .LBB0_496
	v_lshl_add_u64 v[22:23], v[34:35], 2, s[2:3]
	global_load_dwordx4 v[248:251], v[22:23], off
	global_load_dwordx4 v[252:255], v[22:23], off offset:16
	v_mov_b64_e32 v[32:33], v[16:17]
	v_mov_b64_e32 v[30:31], v[14:15]
	v_mov_b64_e32 v[28:29], v[12:13]
	v_mov_b64_e32 v[26:27], v[10:11]
	v_mov_b64_e32 v[24:25], v[8:9]
	v_mov_b64_e32 v[22:23], v[6:7]
	v_mov_b64_e32 v[20:21], v[4:5]
	v_mov_b64_e32 v[18:19], v[2:3]
	s_and_saveexec_b64 s[6:7], s[44:45]
	s_cbranch_execz .LBB0_490
	v_mov_b32_e32 v41, v0
	v_lshl_add_u64 v[26:27], s[2:3], 0, v[40:41]
	v_add_co_u32_e32 v28, vcc, 0x4000, v26
	s_nop 1
	v_addc_co_u32_e32 v29, vcc, 0, v27, vcc
	v_add_co_u32_e32 v50, vcc, 0x5000, v26
	global_load_dword v18, v[28:29], off
	global_load_dword v19, v[28:29], off offset:256
	global_load_dword v20, v[28:29], off offset:512
	global_load_dword v21, v[28:29], off offset:768
	global_load_dword v22, v[28:29], off offset:2048
	global_load_dword v23, v[28:29], off offset:2304
	global_load_dword v24, v[28:29], off offset:2560
	global_load_dword v25, v[28:29], off offset:2816
	v_addc_co_u32_e32 v51, vcc, 0, v27, vcc
	global_load_dword v26, v[50:51], off
	global_load_dword v27, v[50:51], off offset:256
	global_load_dword v28, v[50:51], off offset:512
	global_load_dword v29, v[50:51], off offset:768
	global_load_dword v30, v[50:51], off offset:2048
	global_load_dword v31, v[50:51], off offset:2304
	global_load_dword v32, v[50:51], off offset:2560
	global_load_dword v33, v[50:51], off offset:2816
.LBB0_490:
	s_or_b64 exec, exec, s[6:7]
	s_waitcnt vmcnt(0)
	ds_write_b128 v42, v[248:251] offset:32768
	ds_write_b128 v42, v[252:255] offset:32784
	v_add_u32_e32 v41, v37, v43
	s_waitcnt lgkmcnt(0)
	s_barrier
	ds_read2_b32 v[50:51], v41 offset1:1
	ds_read2_b32 v[52:53], v41 offset0:2 offset1:3
	v_lshl_add_u64 v[54:55], v[38:39], 2, s[2:3]
	v_lshlrev_b32_e32 v56, 2, v36
	v_mov_b32_e32 v57, v0
	v_lshl_add_u64 v[54:55], v[54:55], 0, v[56:57]
	s_mov_b64 s[6:7], 0x4000
	v_lshl_add_u64 v[56:57], v[54:55], 0, s[6:7]
	v_add_co_u32_e32 v54, vcc, 0x4000, v54
	s_nop 1
	v_addc_co_u32_e32 v55, vcc, 0, v55, vcc
	s_waitcnt lgkmcnt(0)
	global_store_dwordx4 v[54:55], v[50:53], off
	ds_read2_b32 v[50:51], v41 offset0:4 offset1:5
	ds_read2_b32 v[52:53], v41 offset0:6 offset1:7
	s_waitcnt lgkmcnt(0)
	global_store_dwordx4 v[56:57], v[50:53], off offset:16
	s_and_saveexec_b64 s[6:7], s[44:45]
	s_cbranch_execz .LBB0_493
	s_mov_b32 s18, 0
	v_mov_b32_e32 v41, v47
	v_add_u32_e32 v49, s18, v44
	ds_read2_b32 v[50:51], v49 offset1:2
	ds_read2st64_b32 v[52:53], v41 offset1:2
.LBB0_492:
	ds_read2_b32 v[54:55], v49 offset0:4 offset1:6
	ds_read2st64_b32 v[56:57], v41 offset0:4 offset1:6
	s_add_i32 s18, s18, 64
	s_waitcnt vmcnt(2) lgkmcnt(2)
	v_mfma_f32_32x32x2_f32 v[18:33], v50, v52, v[18:33]
	v_mfma_f32_32x32x2_f32 v[18:33], v51, v53, v[18:33]
	ds_read2_b32 v[50:51], v49 offset0:8 offset1:10
	ds_read2st64_b32 v[52:53], v41 offset0:8 offset1:10
	s_waitcnt lgkmcnt(2)
	v_mfma_f32_32x32x2_f32 v[18:33], v54, v56, v[18:33]
	v_mfma_f32_32x32x2_f32 v[18:33], v55, v57, v[18:33]
	ds_read2_b32 v[54:55], v49 offset0:12 offset1:14
	ds_read2st64_b32 v[56:57], v41 offset0:12 offset1:14
	v_add_u32_e32 v41, 0x1000, v41
	v_add_u32_e32 v49, s18, v44
	s_waitcnt lgkmcnt(2)
	v_mfma_f32_32x32x2_f32 v[18:33], v50, v52, v[18:33]
	v_mfma_f32_32x32x2_f32 v[18:33], v51, v53, v[18:33]
	ds_read2_b32 v[50:51], v49 offset1:2
	ds_read2st64_b32 v[52:53], v41 offset1:2
	s_cmpk_lg_i32 s18, 0x100
	s_waitcnt lgkmcnt(2)
	v_mfma_f32_32x32x2_f32 v[18:33], v54, v56, v[18:33]
	v_mfma_f32_32x32x2_f32 v[18:33], v55, v57, v[18:33]
	s_cbranch_scc1 .LBB0_492
	s_waitcnt lgkmcnt(0)

; #define LAS __attribute__((address_space(3)))
; __device__ __forceinline__ unsigned pk2(float lo, float hi) { const f32v2_t v = {lo, hi}; const bf16v2_t b = __builtin_convertvector(v, bf16v2_t); return __builtin_bit_cast(unsigned, b); }
; __device__ __forceinline__ float fast_tanh(float x) { return 1.f - 2.f * __builtin_amdgcn_rcpf(1.f + __expf(2.f * x)); }
; __device__ __forceinline__ f32x4 ts4_apply(const RawQ& q, const LAS float* MU, int grp, int col) {
;     const f32x4 pc = {bf2f(q.c.x & 0xffffu), bf2f(q.c.x >> 16), bf2f(q.c.y & 0xffffu), bf2f(q.c.y >> 16)};
;     const f32x4 pp = {bf2f(q.p.x & 0xffffu), bf2f(q.p.x >> 16), bf2f(q.p.y & 0xffffu), bf2f(q.p.y >> 16)};
;     const f32x4 pn = {bf2f(q.n.x & 0xffffu), bf2f(q.n.x >> 16), bf2f(q.n.y & 0xffffu), bf2f(q.n.y >> 16)};
;     const f32x4 m0 = *(const LAS f32x4*)(MU + (grp * 2) * 64 + col), m1 = *(const LAS f32x4*)(MU + (grp * 2 + 1) * 64 + col);
;     return pc + m0 * (pp - pc) + m1 * (pn - pc);
; template <int NV, bool FULL> __device__ __forceinline__ void scan_prep(const ScanLds& L, Raw& R, const bf16* P, const float* mu, int s0, int len, int pos0_next, bool has_next, int h, int dir, const ScanCh& ch, bool doG, int tid_, int wave, int lane_) {
;     ...
;         if (FULL) *(LAS f32x4*)(L.Rs + t * 64 + cq) = ts4_apply(R.q[0], MU, 0, cq);
;         *(LAS f32x4*)(L.KRs + t * 64 + cq) = ts4_apply(R.q[1], MU, 1, cq);
;         *(LAS f32x4*)(L.Vs + t * 64 + cq) = ts4_apply(R.q[2], MU, 2, cq);
;         const f32x4 dw = ts4_apply(R.q[3], MU, 3, cq), da = ts4_apply(R.q[4], MU, 4, cq);
;         v2u w; w.x = pk2(fast_tanh(dw.x), fast_tanh(dw.y)); w.y = pk2(fast_tanh(dw.z), fast_tanh(dw.w)); *(LAS v2u*)(L.DWb + t * 72 + cq) = w;
;         v2u x; x.x = pk2(da.x, da.y); x.y = pk2(da.z, da.w); *(LAS v2u*)(L.DAb + t * 72 + cq) = x;
.LBB0_671:
	v_mov_b32_e32 v18, v82
	v_mov_b32_e32 v24, v183
	s_waitcnt lgkmcnt(0)
	v_and_b32_e32 v25, 15, v18
	v_lshl_add_u32 v40, v25, 4, 0
	v_ashrrev_i32_e32 v1, 4, v18
	v_add_u32_e32 v18, 0x24000, v40
	v_add_u32_e32 v26, 0x24100, v40
	s_barrier
	ds_read_b128 v[18:21], v18
	ds_read_b128 v[26:29], v26
	v_lshlrev_b32_e32 v22, 16, v120
	v_and_b32_e32 v23, 0xffff0000, v120
	v_lshlrev_b32_e32 v30, 16, v121
	v_and_b32_e32 v31, 0xffff0000, v121
	v_lshlrev_b32_e32 v32, 16, v124
	v_and_b32_e32 v33, 0xffff0000, v124
	v_lshlrev_b32_e32 v34, 16, v125
	v_and_b32_e32 v35, 0xffff0000, v125
	v_lshlrev_b32_e32 v36, 16, v126
	v_and_b32_e32 v37, 0xffff0000, v126
	v_lshlrev_b32_e32 v38, 16, v127
	v_and_b32_e32 v39, 0xffff0000, v127
	v_pk_add_f32 v[32:33], v[32:33], v[22:23] neg_lo:[0,1] neg_hi:[0,1]
	v_pk_add_f32 v[34:35], v[34:35], v[30:31] neg_lo:[0,1] neg_hi:[0,1]
	s_waitcnt lgkmcnt(1)
	v_pk_fma_f32 v[20:21], v[34:35], v[20:21], v[30:31]
	v_pk_fma_f32 v[18:19], v[32:33], v[18:19], v[22:23]
	v_pk_add_f32 v[30:31], v[38:39], v[30:31] neg_lo:[0,1] neg_hi:[0,1]
	v_pk_add_f32 v[22:23], v[36:37], v[22:23] neg_lo:[0,1] neg_hi:[0,1]
	s_waitcnt lgkmcnt(0)
	v_pk_fma_f32 v[18:19], v[22:23], v[26:27], v[18:19]
	v_pk_fma_f32 v[20:21], v[30:31], v[28:29], v[20:21]
	v_lshl_add_u32 v36, v1, 8, v40
	ds_write_b128 v36, v[18:21] offset:36864
	v_add_u32_e32 v18, 0x24200, v40
	v_add_u32_e32 v26, 0x24300, v40
	ds_read_b128 v[18:21], v18
	ds_read_b128 v[26:29], v26
	v_lshlrev_b32_e32 v22, 16, v130
	v_and_b32_e32 v23, 0xffff0000, v130
	v_lshlrev_b32_e32 v30, 16, v131
	v_and_b32_e32 v31, 0xffff0000, v131
	v_lshlrev_b32_e32 v32, 16, v132
	v_and_b32_e32 v33, 0xffff0000, v132
	v_lshlrev_b32_e32 v34, 16, v133
	v_and_b32_e32 v35, 0xffff0000, v133
	v_lshlrev_b32_e32 v37, 16, v134
	v_and_b32_e32 v38, 0xffff0000, v134
	v_lshlrev_b32_e32 v39, 16, v135
	v_and_b32_e32 v41, 0xffff0000, v135
	v_pk_add_f32 v[32:33], v[32:33], v[22:23] neg_lo:[0,1] neg_hi:[0,1]
	v_pk_add_f32 v[34:35], v[34:35], v[30:31] neg_lo:[0,1] neg_hi:[0,1]
	s_waitcnt lgkmcnt(1)
	v_pk_fma_f32 v[20:21], v[34:35], v[20:21], v[30:31]
	v_pk_fma_f32 v[18:19], v[32:33], v[18:19], v[22:23]
	v_sub_f32_e32 v31, v41, v31
	v_sub_f32_e32 v30, v39, v30
	v_sub_f32_e32 v23, v38, v23
	v_sub_f32_e32 v22, v37, v22
	s_waitcnt lgkmcnt(0)
	v_pk_fma_f32 v[18:19], v[22:23], v[26:27], v[18:19]
	v_pk_fma_f32 v[20:21], v[30:31], v[28:29], v[20:21]
	ds_write_b128 v36, v[18:21] offset:45056
	v_add_u32_e32 v18, 0x24400, v40
	v_add_u32_e32 v26, 0x24500, v40
	ds_read_b128 v[18:21], v18
	ds_read_b128 v[26:29], v26
	v_lshlrev_b32_e32 v22, 16, v136
	v_and_b32_e32 v23, 0xffff0000, v136
	v_lshlrev_b32_e32 v30, 16, v137
	v_and_b32_e32 v31, 0xffff0000, v137
	v_lshlrev_b32_e32 v32, 16, v138
	v_and_b32_e32 v33, 0xffff0000, v138
	v_lshlrev_b32_e32 v34, 16, v139
	v_and_b32_e32 v35, 0xffff0000, v139
	v_lshlrev_b32_e32 v37, 16, v140
	v_and_b32_e32 v38, 0xffff0000, v140
	v_lshlrev_b32_e32 v39, 16, v141
	v_and_b32_e32 v41, 0xffff0000, v141
	v_pk_add_f32 v[32:33], v[32:33], v[22:23] neg_lo:[0,1] neg_hi:[0,1]
	v_pk_add_f32 v[34:35], v[34:35], v[30:31] neg_lo:[0,1] neg_hi:[0,1]
	s_waitcnt lgkmcnt(1)
	v_pk_fma_f32 v[20:21], v[34:35], v[20:21], v[30:31]
	v_pk_fma_f32 v[18:19], v[32:33], v[18:19], v[22:23]
	v_sub_f32_e32 v31, v41, v31
	v_sub_f32_e32 v30, v39, v30
	v_sub_f32_e32 v23, v38, v23
	v_sub_f32_e32 v22, v37, v22
	s_waitcnt lgkmcnt(0)
	v_pk_fma_f32 v[18:19], v[22:23], v[26:27], v[18:19]
	v_pk_fma_f32 v[20:21], v[30:31], v[28:29], v[20:21]
	ds_write_b128 v36, v[18:21] offset:53248
	v_add_u32_e32 v18, 0x24600, v40
	v_add_u32_e32 v26, 0x24700, v40
	ds_read_b128 v[18:21], v18
	ds_read_b128 v[26:29], v26
	v_lshlrev_b32_e32 v22, 16, v142
	v_and_b32_e32 v23, 0xffff0000, v142
	v_lshlrev_b32_e32 v34, 16, v144
	v_and_b32_e32 v35, 0xffff0000, v144
	v_lshlrev_b32_e32 v30, 16, v143
	v_and_b32_e32 v31, 0xffff0000, v143
	v_lshlrev_b32_e32 v32, 16, v145
	v_and_b32_e32 v33, 0xffff0000, v145
	v_lshlrev_b32_e32 v36, 16, v160
	v_and_b32_e32 v37, 0xffff0000, v160
	v_pk_add_f32 v[34:35], v[34:35], v[22:23] neg_lo:[0,1] neg_hi:[0,1]
	v_lshlrev_b32_e32 v38, 16, v161
	v_and_b32_e32 v39, 0xffff0000, v161
	v_pk_add_f32 v[32:33], v[32:33], v[30:31] neg_lo:[0,1] neg_hi:[0,1]
	s_waitcnt lgkmcnt(1)
	v_pk_fma_f32 v[18:19], v[34:35], v[18:19], v[22:23]
	v_pk_add_f32 v[22:23], v[36:37], v[22:23] neg_lo:[0,1] neg_hi:[0,1]
	v_pk_fma_f32 v[20:21], v[32:33], v[20:21], v[30:31]
	v_pk_add_f32 v[30:31], v[38:39], v[30:31] neg_lo:[0,1] neg_hi:[0,1]
	s_waitcnt lgkmcnt(0)
	v_pk_fma_f32 v[22:23], v[22:23], v[26:27], v[18:19]
	v_add_u32_e32 v18, 0x24800, v40
	v_add_u32_e32 v26, 0x24900, v40
	v_pk_fma_f32 v[30:31], v[30:31], v[28:29], v[20:21]
	ds_read_b128 v[18:21], v18
	ds_read_b128 v[26:29], v26
	v_lshlrev_b32_e32 v34, 16, v163
	v_and_b32_e32 v35, 0xffff0000, v163
	v_lshlrev_b32_e32 v36, 16, v165
	v_and_b32_e32 v37, 0xffff0000, v165
	v_lshlrev_b32_e32 v43, 16, v167
	v_and_b32_e32 v44, 0xffff0000, v167
	v_pk_add_f32 v[36:37], v[36:37], v[34:35] neg_lo:[0,1] neg_hi:[0,1]
	s_waitcnt lgkmcnt(1)
	v_pk_fma_f32 v[20:21], v[36:37], v[20:21], v[34:35]
	v_sub_f32_e32 v35, v44, v35
	v_sub_f32_e32 v34, v43, v34
	v_add_f32_e32 v22, v22, v22
	v_add_f32_e32 v23, v23, v23
	s_waitcnt lgkmcnt(0)
	v_pk_fma_f32 v[20:21], v[34:35], v[28:29], v[20:21]
	v_add_f32_e32 v28, v30, v30
	v_add_f32_e32 v29, v31, v31
	v_mul_f32_e32 v22, 0x3fb8aa3b, v22
	v_mul_f32_e32 v23, 0x3fb8aa3b, v23
	v_mul_f32_e32 v28, 0x3fb8aa3b, v28
	v_mul_f32_e32 v29, 0x3fb8aa3b, v29
	v_exp_f32_e32 v22, v22
	v_exp_f32_e32 v23, v23
	v_exp_f32_e32 v28, v28
	v_exp_f32_e32 v29, v29
	v_add_f32_e32 v22, 1.0, v22
	v_add_f32_e32 v23, 1.0, v23
	v_add_f32_e32 v28, 1.0, v28
	v_add_f32_e32 v29, 1.0, v29
	v_rcp_f32_e32 v22, v22
	v_rcp_f32_e32 v23, v23
	v_rcp_f32_e32 v28, v28
	v_rcp_f32_e32 v29, v29
	v_lshlrev_b32_e32 v32, 16, v162
	v_and_b32_e32 v33, 0xffff0000, v162
	v_lshlrev_b32_e32 v38, 16, v164
	v_and_b32_e32 v39, 0xffff0000, v164
	v_lshlrev_b32_e32 v41, 16, v166
	v_and_b32_e32 v42, 0xffff0000, v166
	v_pk_add_f32 v[38:39], v[38:39], v[32:33] neg_lo:[0,1] neg_hi:[0,1]
	v_pk_fma_f32 v[18:19], v[38:39], v[18:19], v[32:33]
	v_sub_f32_e32 v33, v42, v33
	v_sub_f32_e32 v32, v41, v32
	v_pk_fma_f32 v[18:19], v[32:33], v[26:27], v[18:19]
	v_pk_fma_f32 v[22:23], v[22:23], 2.0, 1.0 op_sel_hi:[1,0,0] neg_lo:[1,0,0] neg_hi:[1,0,0]
	v_pk_fma_f32 v[26:27], v[28:29], 2.0, 1.0 op_sel_hi:[1,0,0] neg_lo:[1,0,0] neg_hi:[1,0,0]
	v_cvt_pk_bf16_f32 v22, v22, v23
	v_cvt_pk_bf16_f32 v23, v26, v27
	v_mul_lo_u32 v26, v1, s77
	v_lshlrev_b32_e32 v27, 3, v25
	v_add3_u32 v28, s87, v26, v27
	v_cvt_pk_bf16_f32 v18, v18, v19
	v_cvt_pk_bf16_f32 v19, v20, v21
	v_add3_u32 v20, s78, v26, v27
	s_and_b64 vcc, exec, s[50:51]
	ds_write_b64 v28, v[22:23]
	ds_write_b64 v20, v[18:19]
	s_cbranch_vccnz .LBB0_673
; #define LAS __attribute__((address_space(3)))
; __device__ __forceinline__ unsigned pk2(float lo, float hi) { const f32v2_t v = {lo, hi}; const bf16v2_t b = __builtin_convertvector(v, bf16v2_t); return __builtin_bit_cast(unsigned, b); }
; __device__ __forceinline__ float fast_sigmoid(float x) { return __builtin_amdgcn_rcpf(1.f + __expf(-x)); }
; __device__ __forceinline__ f32x4 ts4_apply(const RawQ& q, const LAS float* MU, int grp, int col) {
;     const f32x4 pc = {bf2f(q.c.x & 0xffffu), bf2f(q.c.x >> 16), bf2f(q.c.y & 0xffffu), bf2f(q.c.y >> 16)};
;     const f32x4 pp = {bf2f(q.p.x & 0xffffu), bf2f(q.p.x >> 16), bf2f(q.p.y & 0xffffu), bf2f(q.p.y >> 16)};
;     const f32x4 pn = {bf2f(q.n.x & 0xffffu), bf2f(q.n.x >> 16), bf2f(q.n.y & 0xffffu), bf2f(q.n.y >> 16)};
;     const f32x4 m0 = *(const LAS f32x4*)(MU + (grp * 2) * 64 + col), m1 = *(const LAS f32x4*)(MU + (grp * 2 + 1) * 64 + col);
;     return pc + m0 * (pp - pc) + m1 * (pn - pc);
; template <int NV, bool FULL> __device__ __forceinline__ void scan_prep(const ScanLds& L, Raw& R, const bf16* P, const float* mu, int s0, int len, int pos0_next, bool has_next, int h, int dir, const ScanCh& ch, bool doG, int tid_, int wave, int lane_) {
;     ...
;         if (doG) { const int c8 = (tid & 15) * 8; const f32x4 g0 = ts4_apply(R.g[0], MU, 5 + (c8 >> 6), c8 & 63), g1 = ts4_apply(R.g[1], MU, 5 + (c8 >> 6), (c8 & 63) + 4);
;             v4u gq; gq.x = pk2(fast_sigmoid(g0.x), fast_sigmoid(g0.y)); gq.y = pk2(fast_sigmoid(g0.z), fast_sigmoid(g0.w)); gq.z = pk2(fast_sigmoid(g1.x), fast_sigmoid(g1.y)); gq.w = pk2(fast_sigmoid(g1.z), fast_sigmoid(g1.w));
;             *(LAS v4u*)(L.DGb + t * 136 + c8) = gq; }
	v_lshlrev_b32_e32 v18, 6, v25
	v_lshlrev_b32_e32 v19, 5, v25
	v_and_b32_e32 v18, 0x200, v18
	v_and_b32_e32 v19, 0xe0, v19
	v_add3_u32 v44, s61, v18, v19
	ds_read_b128 v[18:21], v44 offset:2560
	ds_read_b128 v[26:29], v44 offset:2576
	ds_read_b128 v[30:33], v44 offset:2816
	v_lshlrev_b32_e32 v22, 16, v112
	v_and_b32_e32 v23, 0xffff0000, v112
	v_lshlrev_b32_e32 v34, 16, v113
	v_and_b32_e32 v35, 0xffff0000, v113
	v_lshlrev_b32_e32 v38, 16, v114
	v_and_b32_e32 v39, 0xffff0000, v114
	v_lshlrev_b32_e32 v36, 16, v115
	v_and_b32_e32 v37, 0xffff0000, v115
	v_pk_add_f32 v[36:37], v[36:37], v[34:35] neg_lo:[0,1] neg_hi:[0,1]
	v_pk_add_f32 v[38:39], v[38:39], v[22:23] neg_lo:[0,1] neg_hi:[0,1]
	v_lshlrev_b32_e32 v40, 16, v116
	v_and_b32_e32 v41, 0xffff0000, v116
	s_waitcnt lgkmcnt(2)
	v_pk_fma_f32 v[38:39], v[38:39], v[18:19], v[22:23]
	v_pk_fma_f32 v[36:37], v[36:37], v[20:21], v[34:35]
	ds_read_b128 v[18:21], v44 offset:2832
	v_pk_add_f32 v[22:23], v[40:41], v[22:23] neg_lo:[0,1] neg_hi:[0,1]
	s_waitcnt lgkmcnt(1)
	v_pk_fma_f32 v[22:23], v[22:23], v[30:31], v[38:39]
	v_lshlrev_b32_e32 v30, 16, v118
	v_and_b32_e32 v31, 0xffff0000, v118
	v_lshlrev_b32_e32 v38, 16, v122
	v_and_b32_e32 v39, 0xffff0000, v122
	v_lshlrev_b32_e32 v40, 16, v128
	v_and_b32_e32 v41, 0xffff0000, v128
	v_pk_add_f32 v[38:39], v[38:39], v[30:31] neg_lo:[0,1] neg_hi:[0,1]
	v_pk_fma_f32 v[26:27], v[38:39], v[26:27], v[30:31]
	v_pk_add_f32 v[30:31], v[40:41], v[30:31] neg_lo:[0,1] neg_hi:[0,1]
	s_waitcnt lgkmcnt(0)
	v_pk_fma_f32 v[18:19], v[30:31], v[18:19], v[26:27]
	v_lshlrev_b32_e32 v42, 16, v117
	v_and_b32_e32 v43, 0xffff0000, v117
	v_mul_f32_e32 v18, 0xbfb8aa3b, v18
	v_pk_add_f32 v[34:35], v[42:43], v[34:35] neg_lo:[0,1] neg_hi:[0,1]
	v_exp_f32_e32 v18, v18
	v_mul_f32_e32 v19, 0xbfb8aa3b, v19
	v_pk_fma_f32 v[32:33], v[34:35], v[32:33], v[36:37]
	v_lshlrev_b32_e32 v34, 16, v119
	v_and_b32_e32 v35, 0xffff0000, v119
	v_lshlrev_b32_e32 v36, 16, v123
	v_and_b32_e32 v37, 0xffff0000, v123
	v_exp_f32_e32 v19, v19
	v_lshlrev_b32_e32 v42, 16, v129
	v_and_b32_e32 v43, 0xffff0000, v129
	v_pk_add_f32 v[36:37], v[36:37], v[34:35] neg_lo:[0,1] neg_hi:[0,1]
	v_pk_fma_f32 v[28:29], v[36:37], v[28:29], v[34:35]
	v_pk_add_f32 v[34:35], v[42:43], v[34:35] neg_lo:[0,1] neg_hi:[0,1]
	v_pk_fma_f32 v[20:21], v[34:35], v[20:21], v[28:29]
	v_add_f32_e32 v18, 1.0, v18
	v_mul_f32_e32 v22, 0xbfb8aa3b, v22
	v_mul_f32_e32 v23, 0xbfb8aa3b, v23
	v_rcp_f32_e32 v28, v18
	v_add_f32_e32 v18, 1.0, v19
	v_mul_f32_e32 v19, 0xbfb8aa3b, v20
	v_exp_f32_e32 v22, v22
	v_exp_f32_e32 v23, v23
	v_mul_f32_e32 v26, 0xbfb8aa3b, v32
	v_mul_f32_e32 v27, 0xbfb8aa3b, v33
	v_exp_f32_e32 v19, v19
	v_mul_f32_e32 v20, 0xbfb8aa3b, v21
	v_exp_f32_e32 v26, v26
	v_exp_f32_e32 v27, v27
	v_exp_f32_e32 v20, v20
	v_add_f32_e32 v22, 1.0, v22
	v_add_f32_e32 v23, 1.0, v23
	v_rcp_f32_e32 v21, v18
	v_add_f32_e32 v18, 1.0, v19
	v_rcp_f32_e32 v22, v22
	v_rcp_f32_e32 v23, v23
	v_add_f32_e32 v26, 1.0, v26
	v_add_f32_e32 v27, 1.0, v27
	v_rcp_f32_e32 v29, v18
	v_add_f32_e32 v18, 1.0, v20
	v_rcp_f32_e32 v26, v26
	v_rcp_f32_e32 v27, v27
	v_rcp_f32_e32 v30, v18
	v_cvt_pk_bf16_f32 v18, v22, v23
	v_mul_lo_u32 v22, v1, s31
	v_lshlrev_b32_e32 v23, 4, v25
	v_cvt_pk_bf16_f32 v19, v26, v27
	v_cvt_pk_bf16_f32 v20, v28, v21
	v_cvt_pk_bf16_f32 v21, v29, v30
	v_add3_u32 v22, s33, v22, v23
	ds_write_b128 v22, v[18:21]

; __device__ __forceinline__ float red16(float p) { p += dpp_f<0xB1>(p); p += dpp_f<0x4E>(p); p += dpp_f<0x141>(p); p += dpp_f<0x140>(p); return p; }
; __device__ __forceinline__ float fast_sigmoid(float x) { return __builtin_amdgcn_rcpf(1.f + __expf(-x)); }
; template <int NV, bool FULL> __device__ __forceinline__ void scan_prep(const ScanLds& L, Raw& R, const bf16* P, const float* mu, int s0, int len, int pos0_next, bool has_next, int h, int dir, const ScanCh& ch, bool doG, int tid_, int wave, int lane_) {
;     ...
;     float ld[4], kkr[4], av4[4], kd[4], rr[4], vv[4];
; #pragma unroll
;     for (int r = 0; r < 4; ++r) { const int t = t0 + r;
;         ld[r] = -0.60653065971f * fast_sigmoid(alw[r] + ch.w0v);
;         av4[r] = fast_sigmoid(ala[r] + ch.a0v);
;         const float kraw = L.KRs[t * 64 + c]; kkr[r] = kraw * ch.kkw; kd[r] = kraw * (1.f + (av4[r] - 1.f) * ch.kaw);
;         rr[r] = FULL ? L.Rs[t * 64 + c] : 0.f; vv[r] = L.Vs[t * 64 + c];
;         const float pk = red16(kkr[r] * kkr[r]); if (l15 == 0) PK[t * 4 + cqw] = pk;
;         if (FULL) { const float ps = red16(rr[r] * kd[r] * ch.rkw); if (l15 == 0) PSB[t * 4 + cqw] = ps; } }
.LBB0_706:
	v_lshlrev_b32_e32 v34, 8, v46
	v_or_b32_e32 v1, v34, v26
	v_lshl_add_u32 v1, v1, 2, 0
	ds_read2st64_b32 v[36:37], v1 offset0:144 offset1:176
	ds_read_b32 v1, v1 offset:53248
	v_cmp_eq_u32_e32 vcc, 0, v47
	s_waitcnt lgkmcnt(1)
	v_mul_f32_e32 v55, v206, v37
	v_mul_f32_e32 v27, v55, v55
	s_nop 1
	v_mov_b32_dpp v27, v27 quad_perm:[1,0,3,2] row_mask:0xf bank_mask:0xf bound_ctrl:1
	v_fmac_f32_e32 v27, v55, v55
	s_nop 1
	v_add_f32_dpp v27, v27, v27 quad_perm:[2,3,0,1] row_mask:0xf bank_mask:0xf bound_ctrl:1
	s_nop 1
	v_add_f32_dpp v28, v27, v27 row_half_mirror row_mask:0xf bank_mask:0xf bound_ctrl:1
	v_lshl_add_u32 v27, v46, 6, s80
	s_nop 0
	v_mov_b32_dpp v29, v28 row_mirror row_mask:0xf bank_mask:0xf bound_ctrl:1
	s_and_saveexec_b64 s[0:1], vcc
	v_add_f32_e32 v28, v28, v29
	ds_write_b32 v27, v28 offset:61440
	s_or_b64 exec, exec, s[0:1]
	v_add_f32_e32 v22, v210, v22
	v_mul_f32_e32 v22, 0xbfb8aa3b, v22
	v_exp_f32_e32 v22, v22
	s_nop 0
	v_add_f32_e32 v22, 1.0, v22
	v_rcp_f32_e32 v56, v22
	s_nop 0
	v_add_f32_e32 v22, -1.0, v56
	v_fma_f32 v22, v207, v22, 1.0
	v_mul_f32_e32 v22, v22, v37
	v_mul_f32_e32 v28, v36, v22
	v_mul_f32_e32 v29, v208, v28
	s_nop 1
	v_mov_b32_dpp v29, v29 quad_perm:[1,0,3,2] row_mask:0xf bank_mask:0xf bound_ctrl:1
	v_fmac_f32_e32 v29, v208, v28
	s_nop 1
	v_add_f32_dpp v28, v29, v29 quad_perm:[2,3,0,1] row_mask:0xf bank_mask:0xf bound_ctrl:1
	s_nop 1
	v_add_f32_dpp v28, v28, v28 row_half_mirror row_mask:0xf bank_mask:0xf bound_ctrl:1
	s_nop 1
	v_mov_b32_dpp v29, v28 row_mirror row_mask:0xf bank_mask:0xf bound_ctrl:1
	s_and_saveexec_b64 s[0:1], vcc
	v_add_f32_e32 v28, v28, v29
	ds_write_b32 v27, v28 offset:61952
	s_or_b64 exec, exec, s[0:1]
	v_lshlrev_b32_e32 v44, 2, v46
	v_or_b32_e32 v37, 1, v44
	v_lshlrev_b32_e32 v28, 2, v26
	v_lshl_or_b32 v27, v37, 8, v28
	v_add_u32_e32 v27, 0, v27
	ds_read2st64_b32 v[32:33], v27 offset0:144 offset1:176
	ds_read_b32 v27, v27 offset:53248
	s_waitcnt lgkmcnt(1)
	v_mul_f32_e32 v49, v206, v33
	v_mul_f32_e32 v29, v49, v49
	s_nop 1
	v_mov_b32_dpp v29, v29 quad_perm:[1,0,3,2] row_mask:0xf bank_mask:0xf bound_ctrl:1
	v_fmac_f32_e32 v29, v49, v49
	s_nop 1
	v_add_f32_dpp v29, v29, v29 quad_perm:[2,3,0,1] row_mask:0xf bank_mask:0xf bound_ctrl:1
	s_nop 1
	v_add_f32_dpp v30, v29, v29 row_half_mirror row_mask:0xf bank_mask:0xf bound_ctrl:1
	v_lshl_add_u32 v29, v37, 4, s80
	s_nop 0
	v_mov_b32_dpp v31, v30 row_mirror row_mask:0xf bank_mask:0xf bound_ctrl:1
	s_and_saveexec_b64 s[0:1], vcc
	v_add_f32_e32 v30, v30, v31
	ds_write_b32 v29, v30 offset:61440
	s_or_b64 exec, exec, s[0:1]
	v_add_f32_e32 v23, v210, v23
	v_mul_f32_e32 v23, 0xbfb8aa3b, v23
	v_exp_f32_e32 v23, v23
	s_nop 0
	v_add_f32_e32 v23, 1.0, v23
	v_rcp_f32_e32 v54, v23
	s_nop 0
	v_add_f32_e32 v23, -1.0, v54
	v_fma_f32 v23, v207, v23, 1.0
	v_mul_f32_e32 v23, v23, v33
	v_mul_f32_e32 v30, v32, v23
	v_mul_f32_e32 v31, v208, v30
	s_nop 1
	v_mov_b32_dpp v31, v31 quad_perm:[1,0,3,2] row_mask:0xf bank_mask:0xf bound_ctrl:1
	v_fmac_f32_e32 v31, v208, v30
	s_nop 1
	v_add_f32_dpp v30, v31, v31 quad_perm:[2,3,0,1] row_mask:0xf bank_mask:0xf bound_ctrl:1
	s_nop 1
	v_add_f32_dpp v30, v30, v30 row_half_mirror row_mask:0xf bank_mask:0xf bound_ctrl:1
	s_nop 1
	v_mov_b32_dpp v31, v30 row_mirror row_mask:0xf bank_mask:0xf bound_ctrl:1
	s_and_saveexec_b64 s[0:1], vcc
	v_add_f32_e32 v30, v30, v31
	ds_write_b32 v29, v30 offset:61952
	s_or_b64 exec, exec, s[0:1]
	v_or_b32_e32 v51, 2, v44
	v_lshl_or_b32 v29, v51, 8, v28
	v_add_u32_e32 v29, 0, v29
	ds_read2st64_b32 v[30:31], v29 offset0:144 offset1:176
	ds_read_b32 v45, v29 offset:53248
	s_waitcnt lgkmcnt(1)
	v_mul_f32_e32 v48, v206, v31
	v_mul_f32_e32 v29, v48, v48
	s_nop 1
	v_mov_b32_dpp v29, v29 quad_perm:[1,0,3,2] row_mask:0xf bank_mask:0xf bound_ctrl:1
	v_fmac_f32_e32 v29, v48, v48
	s_nop 1
	v_add_f32_dpp v29, v29, v29 quad_perm:[2,3,0,1] row_mask:0xf bank_mask:0xf bound_ctrl:1
	s_nop 1
	v_add_f32_dpp v33, v29, v29 row_half_mirror row_mask:0xf bank_mask:0xf bound_ctrl:1
	v_lshl_add_u32 v29, v51, 4, s80
	s_nop 0
	v_mov_b32_dpp v35, v33 row_mirror row_mask:0xf bank_mask:0xf bound_ctrl:1
	s_and_saveexec_b64 s[0:1], vcc
	v_add_f32_e32 v33, v33, v35
	ds_write_b32 v29, v33 offset:61440
	s_or_b64 exec, exec, s[0:1]
	v_add_f32_e32 v24, v210, v24
	v_mul_f32_e32 v24, 0xbfb8aa3b, v24
	v_exp_f32_e32 v24, v24
	s_nop 0
	v_add_f32_e32 v24, 1.0, v24
	v_rcp_f32_e32 v53, v24
	s_nop 0
	v_add_f32_e32 v24, -1.0, v53
	v_fma_f32 v24, v207, v24, 1.0
	v_mul_f32_e32 v24, v24, v31
	v_mul_f32_e32 v31, v30, v24
	v_mul_f32_e32 v33, v208, v31
	s_nop 1
	v_mov_b32_dpp v33, v33 quad_perm:[1,0,3,2] row_mask:0xf bank_mask:0xf bound_ctrl:1
	v_fmac_f32_e32 v33, v208, v31
	s_nop 1
	v_add_f32_dpp v31, v33, v33 quad_perm:[2,3,0,1] row_mask:0xf bank_mask:0xf bound_ctrl:1
	s_nop 1
	v_add_f32_dpp v31, v31, v31 row_half_mirror row_mask:0xf bank_mask:0xf bound_ctrl:1
	s_nop 1
	v_mov_b32_dpp v33, v31 row_mirror row_mask:0xf bank_mask:0xf bound_ctrl:1
	s_and_saveexec_b64 s[0:1], vcc
	v_add_f32_e32 v31, v31, v33
	ds_write_b32 v29, v31 offset:61952
	s_or_b64 exec, exec, s[0:1]
	v_or_b32_e32 v50, 3, v44
	v_lshl_or_b32 v28, v50, 8, v28
	v_add_u32_e32 v31, 0, v28
	ds_read2st64_b32 v[28:29], v31 offset0:144 offset1:176
	ds_read_b32 v31, v31 offset:53248
	s_waitcnt lgkmcnt(1)
; #define LAS __attribute__((address_space(3)))
; __device__ __forceinline__ float red16(float p) { p += dpp_f<0xB1>(p); p += dpp_f<0x4E>(p); p += dpp_f<0x141>(p); p += dpp_f<0x140>(p); return p; }
; template <int NV, bool FULL> __device__ __forceinline__ void scan_prep(const ScanLds& L, Raw& R, const bf16* P, const float* mu, int s0, int len, int pos0_next, bool has_next, int h, int dir, const ScanCh& ch, bool doG, int tid_, int wave, int lane_) {
;     ...
;         const float pk = red16(kkr[r] * kkr[r]); if (l15 == 0) PK[t * 4 + cqw] = pk;
;         if (FULL) { const float ps = red16(rr[r] * kd[r] * ch.rkw); if (l15 == 0) PSB[t * 4 + cqw] = ps; } }
;     float pl[4]; pl[0] = ld[0]; pl[1] = pl[0] + ld[1]; pl[2] = pl[1] + ld[2]; pl[3] = pl[2] + ld[3];
;     L.WT[tg * 64 + c] = pl[3];
;     __syncthreads();
;     float off = 0.f, tot = 0.f;
; #pragma unroll
;     for (int w = 0; w < 8; ++w) { const float x = L.WT[w * 64 + c]; tot += x; if (w < tg) off += x; }
;     const float etot = __expf(tot);
;     if (tg == 0) L.Wend[c] = etot;
;     float khv[4], bhv[4]; float e_last = __expf(off);
; #pragma unroll
;     for (int r = 0; r < 4; ++r) { const int t = t0 + r; const float Lc = off + pl[r];
;         const f32x4 p4 = *(const LAS f32x4*)(PK + t * 4); const float kk = kkr[r] * rsqrtf(fmaxf((p4.x + p4.y) + (p4.z + p4.w), 1e-24f)); const float bd = kk * av4[r];
;         if (FULL && cqw == 0 && l15 == 0) { const f32x4 s4 = *(const LAS f32x4*)(PSB + t * 4); L.SBs[t] = (s4.x + s4.y) + (s4.z + s4.w); }
	v_mul_f32_e32 v33, v206, v29
	v_mul_f32_e32 v35, v33, v33
	s_nop 1
	v_mov_b32_dpp v35, v35 quad_perm:[1,0,3,2] row_mask:0xf bank_mask:0xf bound_ctrl:1
	v_fmac_f32_e32 v35, v33, v33
	s_nop 1
	v_add_f32_dpp v35, v35, v35 quad_perm:[2,3,0,1] row_mask:0xf bank_mask:0xf bound_ctrl:1
	s_nop 1
	v_add_f32_dpp v38, v35, v35 row_half_mirror row_mask:0xf bank_mask:0xf bound_ctrl:1
	v_lshl_add_u32 v35, v50, 4, s80
	s_nop 0
	v_mov_b32_dpp v39, v38 row_mirror row_mask:0xf bank_mask:0xf bound_ctrl:1
	s_and_saveexec_b64 s[0:1], vcc
	v_add_f32_e32 v38, v38, v39
	ds_write_b32 v35, v38 offset:61440
	s_or_b64 exec, exec, s[0:1]
	v_add_f32_e32 v25, v210, v25
	v_mul_f32_e32 v25, 0xbfb8aa3b, v25
	v_exp_f32_e32 v25, v25
	s_nop 0
	v_add_f32_e32 v25, 1.0, v25
	v_rcp_f32_e32 v52, v25
	s_nop 0
	v_add_f32_e32 v25, -1.0, v52
	v_fma_f32 v25, v207, v25, 1.0
	v_mul_f32_e32 v25, v25, v29
	v_mul_f32_e32 v29, v28, v25
	v_mul_f32_e32 v38, v208, v29
	s_nop 1
	v_mov_b32_dpp v38, v38 quad_perm:[1,0,3,2] row_mask:0xf bank_mask:0xf bound_ctrl:1
	v_fmac_f32_e32 v38, v208, v29
	s_nop 1
	v_add_f32_dpp v29, v38, v38 quad_perm:[2,3,0,1] row_mask:0xf bank_mask:0xf bound_ctrl:1
	s_nop 1
	v_add_f32_dpp v29, v29, v29 row_half_mirror row_mask:0xf bank_mask:0xf bound_ctrl:1
	s_nop 1
	v_mov_b32_dpp v38, v29 row_mirror row_mask:0xf bank_mask:0xf bound_ctrl:1
	s_and_saveexec_b64 s[0:1], vcc
	v_add_f32_e32 v29, v29, v38
	ds_write_b32 v35, v29 offset:61952
	s_or_b64 exec, exec, s[0:1]
	v_add_f32_e32 v18, v209, v18
	v_add_f32_e32 v19, v209, v19
	v_mul_f32_e32 v18, 0xbfb8aa3b, v18
	v_add_f32_e32 v20, v209, v20
	v_mul_f32_e32 v19, 0xbfb8aa3b, v19
	v_exp_f32_e32 v18, v18
	v_add_f32_e32 v21, v209, v21
	v_mul_f32_e32 v20, 0xbfb8aa3b, v20
	v_exp_f32_e32 v19, v19
	v_mul_f32_e32 v21, 0xbfb8aa3b, v21
	v_exp_f32_e32 v20, v20
	v_exp_f32_e32 v21, v21
	v_add_f32_e32 v18, 1.0, v18
	v_add_f32_e32 v19, 1.0, v19
	v_rcp_f32_e32 v18, v18
	v_add_f32_e32 v20, 1.0, v20
	v_rcp_f32_e32 v19, v19
	v_add_f32_e32 v21, 1.0, v21
	v_rcp_f32_e32 v20, v20
	v_rcp_f32_e32 v21, v21
	v_mul_f32_e32 v59, 0xbf1b4598, v18
	v_fmamk_f32 v58, v19, 0xbf1b4598, v59
	v_lshl_add_u32 v18, v26, 2, 0
	v_fmamk_f32 v57, v20, 0xbf1b4598, v58
	v_add_u32_e32 v19, 0x20e00, v18
	v_fmamk_f32 v29, v21, 0xbf1b4598, v57
	v_add_u32_e32 v20, v19, v34
	ds_write_b32 v20, v29
	s_waitcnt lgkmcnt(0)
	s_barrier
	ds_read2st64_b32 v[34:35], v19 offset1:1
	ds_read2st64_b32 v[42:43], v19 offset0:2 offset1:3
	ds_read2st64_b32 v[40:41], v19 offset0:4 offset1:5
	ds_read2st64_b32 v[38:39], v19 offset0:6 offset1:7
	v_cmp_eq_u32_e32 vcc, 0, v46
	s_waitcnt lgkmcnt(3)
	v_add_f32_e32 v60, 0, v34
	v_add_f32_e32 v19, v60, v35
	s_waitcnt lgkmcnt(2)
	v_add_f32_e32 v19, v19, v42
	v_add_f32_e32 v19, v19, v43
	s_waitcnt lgkmcnt(1)
	v_add_f32_e32 v19, v19, v40
	v_add_f32_e32 v19, v19, v41
	s_waitcnt lgkmcnt(0)
	v_add_f32_e32 v19, v19, v38
	v_add_f32_e32 v19, v19, v39
	v_mul_f32_e32 v19, 0x3fb8aa3b, v19
	v_exp_f32_e32 v34, v19
	s_and_saveexec_b64 s[0:1], vcc
	v_add_u32_e32 v18, 0x21600, v18
	ds_write_b32 v18, v34
	s_or_b64 exec, exec, s[0:1]
	v_lshl_or_b32 v254, s74, 8, v47
	v_lshl_add_u32 v47, v46, 6, 0
	v_cmp_gt_u32_e32 vcc, 4, v254
	ds_read_b128 v[18:21], v47 offset:61440
	s_and_saveexec_b64 s[0:1], vcc
	s_cbranch_execz .LBB0_726
	v_lshl_add_u32 v255, v254, 4, v47
	ds_read_b128 v[62:65], v255 offset:61952
	v_lshl_add_u32 v61, v44, 2, 0
	v_add_u32_e32 v61, 0x21700, v61
	v_lshl_add_u32 v61, v254, 2, v61
	s_waitcnt lgkmcnt(0)
	v_mov_b32_e32 v66, v63
	v_mov_b32_e32 v67, v64
	v_mov_b32_e32 v63, v65
	v_pk_add_f32 v[62:63], v[66:67], v[62:63]
	s_nop 0
	v_add_f32_e32 v47, v62, v63
	ds_write_b32 v61, v47
; #define LAS __attribute__((address_space(3)))
; __device__ __forceinline__ unsigned f2bf(float f) { return pk2(f, f) & 0xffffu; }
; template <int NV, bool FULL> __device__ __forceinline__ void scan_prep(const ScanLds& L, Raw& R, const bf16* P, const float* mu, int s0, int len, int pos0_next, bool has_next, int h, int dir, const ScanCh& ch, bool doG, int tid_, int wave, int lane_) {
;     ...
;     float khv[4], bhv[4]; float e_last = __expf(off);
; #pragma unroll
;     for (int r = 0; r < 4; ++r) { const int t = t0 + r; const float Lc = off + pl[r];
;         const f32x4 p4 = *(const LAS f32x4*)(PK + t * 4); const float kk = kkr[r] * rsqrtf(fmaxf((p4.x + p4.y) + (p4.z + p4.w), 1e-24f)); const float bd = kk * av4[r];
;         if (FULL && cqw == 0 && l15 == 0) { const f32x4 s4 = *(const LAS f32x4*)(PSB + t * 4); L.SBs[t] = (s4.x + s4.y) + (s4.z + s4.w); }
;         const float e_in = __expf(Lc), e_prev = e_last, e_inv = __builtin_amdgcn_rcpf(e_in), e_end = etot * e_inv; e_last = e_in;
;         L.Kap[t * 72 + c] = (bf16)f2bf(kk * e_prev); if (FULL) L.Rt[t * 72 + c] = (bf16)f2bf(rr[r] * e_in);
;         L.Kt[t * 72 + c] = (bf16)f2bf(kd[r] * e_inv); L.Bt[t * 72 + c] = (bf16)f2bf(bd * e_inv);
;         khv[r] = kd[r] * e_end; bhv[r] = -bd * e_end; }
.LBB0_726:
	s_or_b64 exec, exec, s[0:1]
	v_cmp_lt_i32_e64 s[52:53], 0, v46
	s_waitcnt lgkmcnt(0)
	v_add_f32_e32 v18, v18, v19
	v_add_f32_e32 v19, v20, v21
	v_cndmask_b32_e64 v47, 0, v60, s[52:53]
	v_add_f32_e32 v35, v35, v47
	v_cmp_lt_i32_e64 s[52:53], 1, v46
	v_add_f32_e32 v18, v18, v19
	v_max_f32_e32 v18, 0x179abe15, v18
	v_cndmask_b32_e64 v35, v47, v35, s[52:53]
	v_add_f32_e32 v42, v42, v35
	v_cmp_lt_i32_e64 s[52:53], 2, v46
	v_rsq_f32_e32 v18, v18
	s_nop 0
	v_cndmask_b32_e64 v35, v35, v42, s[52:53]
	v_add_f32_e32 v42, v43, v35
	v_cmp_lt_i32_e64 s[52:53], 3, v46
	v_mul_f32_e32 v18, v55, v18
	s_nop 0
	v_cndmask_b32_e64 v35, v35, v42, s[52:53]
	v_add_f32_e32 v40, v40, v35
	v_cmp_lt_i32_e64 s[52:53], 4, v46
	s_nop 1
	v_cndmask_b32_e64 v35, v35, v40, s[52:53]
	v_add_f32_e32 v40, v41, v35
	v_cmp_lt_i32_e64 s[52:53], 5, v46
	s_nop 1
	v_cndmask_b32_e64 v35, v35, v40, s[52:53]
	v_add_f32_e32 v38, v38, v35
	v_cmp_lt_i32_e64 s[52:53], 6, v46
	s_nop 1
	v_cndmask_b32_e64 v35, v35, v38, s[52:53]
	v_add_f32_e32 v38, v39, v35
	v_cmp_lt_i32_e64 s[52:53], 7, v46
	s_nop 1
	v_cndmask_b32_e64 v35, v35, v38, s[52:53]
	v_add_f32_e32 v39, v59, v35
	v_mul_f32_e32 v38, 0x3fb8aa3b, v35
	v_mul_f32_e32 v19, 0x3fb8aa3b, v39
	v_exp_f32_e32 v42, v19
	v_exp_f32_e32 v19, v38
	v_mul_f32_e32 v38, v56, v18
	v_rcp_f32_e32 v40, v42
	v_mul_f32_e32 v18, v19, v18
	v_cvt_pk_bf16_f32 v20, v18, s0
	s_movk_i32 s0, 0x120
	v_mad_u64_u32 v[18:19], s[0:1], v46, s0, v[26:27]
	v_lshl_add_u32 v18, v18, 1, 0
	v_add_u32_e32 v19, 0x17600, v18
	ds_write_b16 v19, v20
	v_mul_f32_e32 v19, v36, v42
	v_cvt_pk_bf16_f32 v19, v19, s0
	v_add_u32_e32 v20, 0x18800, v18
	ds_write_b16 v20, v19
	v_mul_f32_e32 v19, v22, v40
	v_cvt_pk_bf16_f32 v19, v19, s0
	v_add_u32_e32 v20, 0x19a00, v18
	ds_write_b16 v20, v19
	v_mul_f32_e32 v19, v40, v38
	v_cvt_pk_bf16_f32 v19, v19, s0
	v_add_u32_e32 v18, 0x1ac00, v18
	ds_write_b16 v18, v19
	v_lshl_add_u32 v36, v37, 4, 0
	ds_read_b128 v[18:21], v36 offset:61440
	s_and_saveexec_b64 s[0:1], vcc
	s_branch .LBB0_728
	ds_read_b128 v[60:63], v36 offset:61952
	v_lshl_add_u32 v39, v37, 2, 0
	v_add_u32_e32 v39, 0x21700, v39
	s_waitcnt lgkmcnt(0)
	v_mov_b32_e32 v46, v61
	v_mov_b32_e32 v47, v62
	v_mov_b32_e32 v61, v63
	v_pk_add_f32 v[46:47], v[46:47], v[60:61]
	s_nop 0
	v_add_f32_e32 v36, v46, v47
	ds_write_b32 v39, v36
.LBB0_728:
	s_or_b64 exec, exec, s[0:1]
	s_waitcnt lgkmcnt(0)
	v_add_f32_e32 v18, v18, v19
	v_add_f32_e32 v19, v20, v21
	v_add_f32_e32 v18, v18, v19
	v_max_f32_e32 v18, 0x179abe15, v18
	v_add_f32_e32 v36, v58, v35
	v_rsq_f32_e32 v18, v18
	v_mul_f32_e32 v19, 0x3fb8aa3b, v36
	v_exp_f32_e32 v55, v19
	v_mul_f32_e32 v18, v49, v18
	v_mul_f32_e32 v39, v54, v18
	v_mul_f32_e32 v18, v42, v18
	v_rcp_f32_e32 v41, v55
	v_cvt_pk_bf16_f32 v20, v18, s0
	s_movk_i32 s0, 0x48
	v_mad_u64_u32 v[18:19], s[0:1], v37, s0, v[26:27]
	v_lshl_add_u32 v18, v18, 1, 0
	v_mul_f32_e32 v19, v32, v55
	v_cvt_pk_bf16_f32 v19, v19, s0
	v_add_u32_e32 v43, 0x18800, v18
	ds_write_b16 v43, v19
	v_mul_f32_e32 v19, v23, v41
	v_cvt_pk_bf16_f32 v19, v19, s0
	v_add_u32_e32 v46, 0x19a00, v18
	ds_write_b16 v46, v19
	v_mul_f32_e32 v19, v41, v39
	v_add_u32_e32 v42, 0x17600, v18
	v_cvt_pk_bf16_f32 v19, v19, s0
	v_add_u32_e32 v47, 0x1ac00, v18
	ds_write_b16 v42, v20
	ds_write_b16 v47, v19
	v_lshl_add_u32 v32, v51, 4, 0
	ds_read_b128 v[18:21], v32 offset:61440
	s_and_saveexec_b64 s[0:1], vcc
	s_branch .LBB0_730
	ds_read_b128 v[58:61], v32 offset:61952
	v_lshl_add_u32 v32, v51, 2, 0
	v_add_u32_e32 v32, 0x21700, v32
	s_waitcnt lgkmcnt(0)
	v_mov_b32_e32 v36, v59
	v_mov_b32_e32 v37, v60
	v_mov_b32_e32 v59, v61
	v_pk_add_f32 v[36:37], v[36:37], v[58:59]
	s_nop 0
	v_add_f32_e32 v36, v36, v37
	ds_write_b32 v32, v36
.LBB0_730:
	s_or_b64 exec, exec, s[0:1]
	s_waitcnt lgkmcnt(0)
	v_add_f32_e32 v18, v18, v19
	v_add_f32_e32 v19, v20, v21
	v_add_f32_e32 v18, v18, v19
	v_add_f32_e32 v32, v57, v35
	v_max_f32_e32 v18, 0x179abe15, v18
	v_rsq_f32_e32 v18, v18
	v_mul_f32_e32 v19, 0x3fb8aa3b, v32
	v_exp_f32_e32 v49, v19
	v_mul_f32_e32 v18, v48, v18
	v_mul_f32_e32 v32, v53, v18
	v_rcp_f32_e32 v36, v49
	v_mul_f32_e32 v18, v55, v18
	v_cvt_pk_bf16_f32 v18, v18, s0
	ds_write_b16 v42, v18 offset:144
	v_mul_f32_e32 v18, v30, v49
	v_cvt_pk_bf16_f32 v18, v18, s0
	ds_write_b16 v43, v18 offset:144
	v_mul_f32_e32 v18, v24, v36
	v_cvt_pk_bf16_f32 v18, v18, s0
	ds_write_b16 v46, v18 offset:144
	v_mul_f32_e32 v18, v36, v32
	v_cvt_pk_bf16_f32 v18, v18, s0
	ds_write_b16 v47, v18 offset:144
	v_lshl_add_u32 v30, v50, 4, 0
	ds_read_b128 v[18:21], v30 offset:61440
	s_and_saveexec_b64 s[0:1], vcc
	s_branch .LBB0_732
	ds_read_b128 v[54:57], v30 offset:61952
	v_lshl_add_u32 v30, v50, 2, 0
	v_add_u32_e32 v30, 0x21700, v30
	s_waitcnt lgkmcnt(0)
	v_mov_b32_e32 v50, v55
	v_mov_b32_e32 v51, v56
	v_mov_b32_e32 v55, v57
	v_pk_add_f32 v[50:51], v[50:51], v[54:55]
	s_nop 0
	v_add_f32_e32 v37, v50, v51
	ds_write_b32 v30, v37

; __device__ __forceinline__ int mrow(int r, int hi) { return (r & 3) + 8 * (r >> 2) + 4 * hi; }
; template <int NV, bool WITHY> __device__ __forceinline__ void scan_chunk(const ScanLds& L, f32x16& st, bool hasT, int kt, int vt, int wave, int lane_, bf16* ypark = nullptr) {
;     ...
;     if (wave == 0) {
;         __builtin_amdgcn_s_setprio(3);
; #pragma unroll
;         for (int r = 0; r < 16; ++r) { Q[r] = 0.f; QT[r] = 0.f; }
;         mm32<4>(Q, L.Bt, 72, 0, L.Kap, 72, 0, l31, hi);
;         mm32<4>(QT, L.Kap, 72, 0, L.Bt, 72, 0, l31, hi);
; #pragma unroll
;         for (int r = 0; r < 16; ++r) { const int row = mrow(r, hi); Q[r] = row < l31 ? Q[r] : 0.f; QT[r] = l31 < row ? QT[r] : 0.f; W[r] = (row == l31 ? 1.f : 0.f) - QT[r]; }
;         nat_store(L.BQ, Q, l31, hi); nat_store(L.BQT, QT, l31, hi);
.LBB0_743:
	v_mul_u32_u24_e32 v222, 0x90, v213
	v_lshlrev_b32_e32 v217, 4, v214
	v_mul_u32_u24_e32 v218, 0x50, v213
	v_mov_b32_e32 v18, 0
	s_andn2_b64 vcc, exec, s[0:1]
	v_add3_u32 v223, s5, v222, v217
	v_add3_u32 v220, s21, v218, v215
	v_add3_u32 v221, s20, v218, v215
	v_add3_u32 v219, s34, v218, v215
	s_cbranch_vccz .Lw0skip2
	v_mov_b32_e32 v66, 0
	v_mov_b32_e32 v67, 0
	v_mov_b32_e32 v68, 0
	v_mov_b32_e32 v69, 0
	v_mov_b32_e32 v70, 0
	v_mov_b32_e32 v71, 0
	v_mov_b32_e32 v72, 0
	v_mov_b32_e32 v73, 0
	v_mov_b32_e32 v74, 0
	v_mov_b32_e32 v75, 0
	v_mov_b32_e32 v76, 0
	v_mov_b32_e32 v77, 0
	v_mov_b32_e32 v78, 0
	v_mov_b32_e32 v79, 0
	v_mov_b32_e32 v80, 0
	v_mov_b32_e32 v81, 0
	v_mov_b32_e32 v34, 0
	v_mov_b32_e32 v35, 0
	v_mov_b32_e32 v36, 0
	v_mov_b32_e32 v37, 0
	v_mov_b32_e32 v38, 0
	v_mov_b32_e32 v39, 0
	v_mov_b32_e32 v40, 0
	v_mov_b32_e32 v41, 0
	v_mov_b32_e32 v42, 0
	v_mov_b32_e32 v43, 0
	v_mov_b32_e32 v44, 0
	v_mov_b32_e32 v45, 0
	v_mov_b32_e32 v46, 0
	v_mov_b32_e32 v47, 0
	v_mov_b32_e32 v48, 0
	v_mov_b32_e32 v49, 0
	s_branch .LBB0_745
.Lw0skip2:
	s_setprio 3
	v_add3_u32 v19, s57, v222, v217
	ds_read_b128 v[20:23], v19
	ds_read_b128 v[24:27], v19 offset:32
	ds_read_b128 v[28:31], v223
	ds_read_b128 v[66:69], v223 offset:32
	ds_read_b128 v[70:73], v19 offset:64
	ds_read_b128 v[74:77], v223 offset:64
	ds_read_b128 v[78:81], v19 offset:96
	ds_read_b128 v[224:227], v223 offset:96
	v_lshlrev_b32_e32 v19, 2, v214
	s_waitcnt lgkmcnt(5)
	v_mfma_f32_32x32x16_bf16 v[50:65], v[28:31], v[20:23], 0
	v_cmp_lt_i32_e64 s[54:55], v213, v19
	v_cmp_lt_i32_e32 vcc, v19, v213
	v_add_u32_e32 v33, 24, v19
	v_add_u32_e32 v32, 25, v19
	v_mfma_f32_32x32x16_bf16 v[34:49], v[20:23], v[28:31], 0
	v_or_b32_e32 v23, 2, v19
	v_or_b32_e32 v22, 3, v19
	v_add_u32_e32 v29, 16, v19
	v_add_u32_e32 v28, 17, v19
	v_add_u32_e32 v31, 18, v19
	v_add_u32_e32 v30, 19, v19
	s_waitcnt lgkmcnt(4)
	v_mfma_f32_32x32x16_bf16 v[50:65], v[66:69], v[24:27], v[50:65]
	v_mfma_f32_32x32x16_bf16 v[34:49], v[24:27], v[66:69], v[34:49]
	v_add_u32_e32 v25, 8, v19
	v_add_u32_e32 v24, 9, v19
	v_add_u32_e32 v27, 10, v19
	v_add_u32_e32 v26, 11, v19
	s_waitcnt lgkmcnt(2)
	v_mfma_f32_32x32x16_bf16 v[50:65], v[74:77], v[70:73], v[50:65]
	v_mfma_f32_32x32x16_bf16 v[34:49], v[70:73], v[74:77], v[34:49]
	s_waitcnt lgkmcnt(0)
	v_mfma_f32_32x32x16_bf16 v[50:65], v[224:227], v[78:81], v[50:65]
	v_mfma_f32_32x32x16_bf16 v[34:49], v[78:81], v[224:227], v[34:49]
	s_nop 10
	v_cndmask_b32_e64 v67, 0, v50, s[54:55]
	v_cmp_eq_u32_e64 s[54:55], v19, v213
	v_cndmask_b32_e64 v68, v51, 0, vcc
	s_nop 0
	v_cndmask_b32_e64 v20, 0, 1.0, s[54:55]
	v_cndmask_b32_e32 v66, 0, v34, vcc
	v_sub_f32_e32 v34, v20, v67
	v_or_b32_e32 v20, 1, v19
	v_cmp_eq_u32_e32 vcc, v20, v213
	v_cmp_lt_i32_e64 s[54:55], v20, v213
	s_nop 0
	v_cndmask_b32_e64 v20, 0, 1.0, vcc
	v_cmp_lt_i32_e32 vcc, v23, v213
	v_cndmask_b32_e64 v50, 0, v35, s[54:55]
	v_sub_f32_e32 v35, v20, v68
	v_cndmask_b32_e32 v51, 0, v36, vcc
	v_cmp_lt_i32_e32 vcc, v213, v23
	v_cmp_lt_i32_e64 s[54:55], v213, v22
	v_cvt_pk_bf16_f32 v50, v66, v50
	v_cndmask_b32_e32 v20, 0, v52, vcc
	v_cmp_lt_i32_e32 vcc, v22, v213
	v_cndmask_b32_e64 v21, 0, v53, s[54:55]
	v_cmp_eq_u32_e64 s[54:55], v22, v213
	v_cndmask_b32_e32 v52, 0, v37, vcc
	v_cmp_eq_u32_e32 vcc, v23, v213
	v_cndmask_b32_e64 v23, 0, 1.0, s[54:55]
	v_cmp_lt_i32_e64 s[54:55], v213, v24
	v_cndmask_b32_e64 v22, 0, 1.0, vcc
	v_cmp_lt_i32_e32 vcc, v25, v213
	v_pk_add_f32 v[36:37], v[22:23], v[20:21] neg_lo:[0,1] neg_hi:[0,1]
	v_cndmask_b32_e64 v23, 0, v55, s[54:55]
	v_cndmask_b32_e32 v53, 0, v38, vcc
	v_cmp_lt_i32_e32 vcc, v213, v25
	v_cmp_eq_u32_e64 s[54:55], v24, v213
	v_cvt_pk_bf16_f32 v51, v51, v52
	v_cndmask_b32_e32 v22, 0, v54, vcc
	v_cmp_lt_i32_e32 vcc, v24, v213
	ds_write_b64 v220, v[50:51]
	s_nop 0
	v_cndmask_b32_e32 v54, 0, v39, vcc
	v_cmp_eq_u32_e32 vcc, v25, v213
	v_cndmask_b32_e64 v25, 0, 1.0, s[54:55]
	v_cmp_lt_i32_e64 s[54:55], v213, v26
	v_cndmask_b32_e64 v24, 0, 1.0, vcc
	v_cmp_lt_i32_e32 vcc, v27, v213
	v_pk_add_f32 v[38:39], v[24:25], v[22:23] neg_lo:[0,1] neg_hi:[0,1]
	v_cndmask_b32_e64 v25, 0, v57, s[54:55]
	v_cndmask_b32_e32 v55, 0, v40, vcc
	v_cmp_lt_i32_e32 vcc, v213, v27
	v_cmp_eq_u32_e64 s[54:55], v26, v213
	v_cvt_pk_bf16_f32 v50, v53, v54
	v_cndmask_b32_e32 v24, 0, v56, vcc
	v_cmp_lt_i32_e32 vcc, v26, v213
	s_nop 1
	v_cndmask_b32_e32 v56, 0, v41, vcc
	v_cmp_eq_u32_e32 vcc, v27, v213
	v_cndmask_b32_e64 v27, 0, 1.0, s[54:55]
	v_cmp_lt_i32_e64 s[54:55], v213, v28
	v_cndmask_b32_e64 v26, 0, 1.0, vcc
	v_cmp_lt_i32_e32 vcc, v29, v213
	v_pk_add_f32 v[40:41], v[26:27], v[24:25] neg_lo:[0,1] neg_hi:[0,1]
	v_cndmask_b32_e64 v27, 0, v59, s[54:55]
	v_cndmask_b32_e32 v57, 0, v42, vcc
	v_cmp_lt_i32_e32 vcc, v213, v29
	v_cmp_eq_u32_e64 s[54:55], v28, v213
	v_cvt_pk_bf16_f32 v51, v55, v56
	v_cndmask_b32_e32 v26, 0, v58, vcc
	v_cmp_lt_i32_e32 vcc, v28, v213
	ds_write_b64 v220, v[50:51] offset:16
	s_nop 0
	v_cndmask_b32_e32 v58, 0, v43, vcc
	v_cmp_eq_u32_e32 vcc, v29, v213
	v_cndmask_b32_e64 v29, 0, 1.0, s[54:55]
	v_cmp_lt_i32_e64 s[54:55], v213, v30
	v_cndmask_b32_e64 v28, 0, 1.0, vcc
	v_cmp_lt_i32_e32 vcc, v31, v213
	v_pk_add_f32 v[42:43], v[28:29], v[26:27] neg_lo:[0,1] neg_hi:[0,1]
	v_cndmask_b32_e64 v29, 0, v61, s[54:55]
	v_cndmask_b32_e32 v59, 0, v44, vcc
	v_cmp_lt_i32_e32 vcc, v213, v31
	v_cmp_eq_u32_e64 s[54:55], v30, v213
	v_cvt_pk_bf16_f32 v50, v57, v58
	v_cndmask_b32_e32 v28, 0, v60, vcc
	v_cmp_lt_i32_e32 vcc, v30, v213
	s_nop 1
	v_cndmask_b32_e32 v60, 0, v45, vcc
	v_cmp_eq_u32_e32 vcc, v31, v213
	v_cndmask_b32_e64 v31, 0, 1.0, s[54:55]
	v_cmp_lt_i32_e64 s[54:55], v213, v32
	v_cndmask_b32_e64 v30, 0, 1.0, vcc
; template <int NV, bool WITHY> __device__ __forceinline__ void scan_chunk(const ScanLds& L, f32x16& st, bool hasT, int kt, int vt, int wave, int lane_, bf16* ypark = nullptr) {
;     ...
;         nat_store(L.BQ, Q, l31, hi); nat_store(L.BQT, QT, l31, hi);
;         {   f32x16 Qn, QTn;
; #pragma unroll
;             for (int r = 0; r < 16; ++r) { Qn[r] = 0.f; QTn[r] = 0.f; }
;             mm32<2>(Qn, L.BQT, 40, 0, L.BQ, 40, 0, l31, hi); mm32<2>(QTn, L.BQ, 40, 0, L.BQT, 40, 0, l31, hi); Q = Qn; QT = QTn; }
; #pragma unroll
;         for (int n = 1; n < 3; ++n) {
;             nat_store(L.BQ, Q, l31, hi); nat_store(L.BQT, QT, l31, hi); nat_store(L.BW, W, l31, hi);
;             f32x16 Qn, QTn;
; #pragma unroll
;             for (int r = 0; r < 16; ++r) { Qn[r] = 0.f; QTn[r] = 0.f; }
;             mm32<2>(W, L.BQ, 40, 0, L.BW, 40, 0, l31, hi); mm32<2>(Qn, L.BQT, 40, 0, L.BQ, 40, 0, l31, hi); mm32<2>(QTn, L.BQ, 40, 0, L.BQT, 40, 0, l31, hi); Q = Qn; QT = QTn; }
	v_cmp_lt_i32_e32 vcc, v33, v213
	v_pk_add_f32 v[44:45], v[30:31], v[28:29] neg_lo:[0,1] neg_hi:[0,1]
	v_cndmask_b32_e64 v31, 0, v63, s[54:55]
	v_cndmask_b32_e32 v61, 0, v46, vcc
	v_cmp_lt_i32_e32 vcc, v213, v33
	v_add_u32_e32 v63, 27, v19
	v_add_u32_e32 v19, 26, v19
	v_cndmask_b32_e32 v30, 0, v62, vcc
	v_cmp_lt_i32_e32 vcc, v32, v213
	v_cmp_eq_u32_e64 s[54:55], v32, v213
	v_cvt_pk_bf16_f32 v51, v59, v60
	v_cndmask_b32_e32 v62, 0, v47, vcc
	v_cmp_eq_u32_e32 vcc, v33, v213
	v_cndmask_b32_e64 v33, 0, 1.0, s[54:55]
	ds_write_b64 v220, v[50:51] offset:32
	v_cndmask_b32_e64 v32, 0, 1.0, vcc
	v_cmp_lt_i32_e32 vcc, v19, v213
	v_pk_add_f32 v[46:47], v[32:33], v[30:31] neg_lo:[0,1] neg_hi:[0,1]
	v_cvt_pk_bf16_f32 v50, v61, v62
	v_cndmask_b32_e32 v69, 0, v48, vcc
	v_cmp_lt_i32_e32 vcc, v213, v19
	v_cmp_lt_i32_e64 s[54:55], v213, v63
	s_nop 0
	v_cndmask_b32_e32 v32, 0, v64, vcc
	v_cmp_lt_i32_e32 vcc, v63, v213
	v_cndmask_b32_e64 v33, 0, v65, s[54:55]
	v_cmp_eq_u32_e64 s[54:55], v63, v213
	v_cndmask_b32_e32 v64, 0, v49, vcc
	v_cvt_pk_bf16_f32 v51, v69, v64
	ds_write_b64 v220, v[50:51] offset:48
	v_cvt_pk_bf16_f32 v51, v20, v21
	v_cvt_pk_bf16_f32 v20, v22, v23
	v_cvt_pk_bf16_f32 v21, v24, v25
	ds_write_b64 v221, v[20:21] offset:16
	v_cvt_pk_bf16_f32 v20, v26, v27
	v_cvt_pk_bf16_f32 v21, v28, v29
	v_cmp_eq_u32_e32 vcc, v19, v213
	v_cvt_pk_bf16_f32 v50, v67, v68
	ds_write_b64 v221, v[20:21] offset:32
	v_cvt_pk_bf16_f32 v20, v30, v31
	v_cvt_pk_bf16_f32 v21, v32, v33
	v_cndmask_b32_e64 v49, 0, 1.0, s[54:55]
	v_cndmask_b32_e64 v48, 0, 1.0, vcc
	ds_write_b64 v221, v[50:51]
	ds_write_b64 v221, v[20:21] offset:48
	v_add_u32_e32 v19, v221, v215
	v_pk_add_f32 v[48:49], v[48:49], v[32:33] neg_lo:[0,1] neg_hi:[0,1]
	v_add_u32_e32 v32, v220, v215
	ds_read_b128 v[20:23], v19
	ds_read_b128 v[24:27], v19 offset:32
	ds_read_b128 v[28:31], v32
	ds_read_b128 v[224:227], v32 offset:32
	s_waitcnt lgkmcnt(1)
	v_mfma_f32_32x32x16_bf16 v[50:65], v[20:23], v[28:31], 0
	v_add_u32_e32 v33, v219, v215
	v_mfma_f32_32x32x16_bf16 v[66:81], v[28:31], v[20:23], 0
	s_waitcnt lgkmcnt(0)
	v_mfma_f32_32x32x16_bf16 v[50:65], v[24:27], v[224:227], v[50:65]
	v_mfma_f32_32x32x16_bf16 v[66:81], v[224:227], v[24:27], v[66:81]
	s_nop 10
	v_cvt_pk_bf16_f32 v20, v50, v51
	v_cvt_pk_bf16_f32 v21, v52, v53
	ds_write_b64 v220, v[20:21]
	v_cvt_pk_bf16_f32 v20, v54, v55
	v_cvt_pk_bf16_f32 v21, v56, v57
	ds_write_b64 v220, v[20:21] offset:16
	v_cvt_pk_bf16_f32 v20, v58, v59
	v_cvt_pk_bf16_f32 v21, v60, v61
	ds_write_b64 v220, v[20:21] offset:32
	v_cvt_pk_bf16_f32 v20, v62, v63
	v_cvt_pk_bf16_f32 v21, v64, v65
	ds_write_b64 v220, v[20:21] offset:48
	v_cvt_pk_bf16_f32 v20, v66, v67
	v_cvt_pk_bf16_f32 v21, v68, v69
	ds_write_b64 v221, v[20:21]
	v_cvt_pk_bf16_f32 v20, v70, v71
	v_cvt_pk_bf16_f32 v21, v72, v73
	ds_write_b64 v221, v[20:21] offset:16
	v_cvt_pk_bf16_f32 v20, v74, v75
	v_cvt_pk_bf16_f32 v21, v76, v77
	ds_write_b64 v221, v[20:21] offset:32
	v_cvt_pk_bf16_f32 v20, v78, v79
	v_cvt_pk_bf16_f32 v21, v80, v81
	ds_write_b64 v221, v[20:21] offset:48
	v_cvt_pk_bf16_f32 v20, v34, v35
	v_cvt_pk_bf16_f32 v21, v36, v37
	ds_write_b64 v219, v[20:21]
	v_cvt_pk_bf16_f32 v20, v38, v39
	v_cvt_pk_bf16_f32 v21, v40, v41
	ds_write_b64 v219, v[20:21] offset:16
	v_cvt_pk_bf16_f32 v20, v42, v43
	v_cvt_pk_bf16_f32 v21, v44, v45
	ds_write_b64 v219, v[20:21] offset:32
	v_cvt_pk_bf16_f32 v20, v46, v47
	v_cvt_pk_bf16_f32 v21, v48, v49
	ds_write_b64 v219, v[20:21] offset:48
	ds_read_b128 v[20:23], v32
	ds_read_b128 v[24:27], v32 offset:32
	ds_read_b128 v[28:31], v33
	ds_read_b128 v[50:53], v33 offset:32
	s_waitcnt lgkmcnt(1)
	v_mfma_f32_32x32x16_bf16 v[34:49], v[20:23], v[28:31], v[34:49]
	ds_read_b128 v[28:31], v19
	ds_read_b128 v[224:227], v19 offset:32
	s_waitcnt lgkmcnt(1)
	v_mfma_f32_32x32x16_bf16 v[66:81], v[28:31], v[20:23], 0
	v_mfma_f32_32x32x16_bf16 v[34:49], v[24:27], v[50:53], v[34:49]
	v_mfma_f32_32x32x16_bf16 v[50:65], v[20:23], v[28:31], 0
	s_waitcnt lgkmcnt(0)
	v_mfma_f32_32x32x16_bf16 v[66:81], v[224:227], v[24:27], v[66:81]
	v_mfma_f32_32x32x16_bf16 v[50:65], v[24:27], v[224:227], v[50:65]
	s_nop 10
	v_cvt_pk_bf16_f32 v20, v66, v67
	v_cvt_pk_bf16_f32 v21, v68, v69
	ds_write_b64 v220, v[20:21]
	v_cvt_pk_bf16_f32 v20, v70, v71
	v_cvt_pk_bf16_f32 v21, v72, v73
	ds_write_b64 v220, v[20:21] offset:16
	v_cvt_pk_bf16_f32 v20, v74, v75
	v_cvt_pk_bf16_f32 v21, v76, v77
	ds_write_b64 v220, v[20:21] offset:32
	v_cvt_pk_bf16_f32 v20, v78, v79
	v_cvt_pk_bf16_f32 v21, v80, v81
	ds_write_b64 v220, v[20:21] offset:48
	v_cvt_pk_bf16_f32 v20, v50, v51
	v_cvt_pk_bf16_f32 v21, v52, v53
	ds_write_b64 v221, v[20:21]
	v_cvt_pk_bf16_f32 v20, v54, v55
	v_cvt_pk_bf16_f32 v21, v56, v57
	ds_write_b64 v221, v[20:21] offset:16
	v_cvt_pk_bf16_f32 v20, v58, v59
	v_cvt_pk_bf16_f32 v21, v60, v61
	ds_write_b64 v221, v[20:21] offset:32
	v_cvt_pk_bf16_f32 v20, v62, v63
	v_cvt_pk_bf16_f32 v21, v64, v65
	ds_write_b64 v221, v[20:21] offset:48
	v_cvt_pk_bf16_f32 v20, v34, v35
	v_cvt_pk_bf16_f32 v21, v36, v37
	ds_write_b64 v219, v[20:21]
	v_cvt_pk_bf16_f32 v20, v38, v39
	v_cvt_pk_bf16_f32 v21, v40, v41
	ds_write_b64 v219, v[20:21] offset:16
	v_cvt_pk_bf16_f32 v20, v42, v43
	v_cvt_pk_bf16_f32 v21, v44, v45
	ds_write_b64 v219, v[20:21] offset:32
	v_cvt_pk_bf16_f32 v20, v46, v47
	v_cvt_pk_bf16_f32 v21, v48, v49
	ds_write_b64 v219, v[20:21] offset:48
	ds_read_b128 v[20:23], v32
	ds_read_b128 v[24:27], v32 offset:32
	ds_read_b128 v[28:31], v33
	ds_read_b128 v[50:53], v33 offset:32
	s_waitcnt lgkmcnt(1)
	v_mfma_f32_32x32x16_bf16 v[34:49], v[20:23], v[28:31], v[34:49]
	ds_read_b128 v[28:31], v19
	ds_read_b128 v[224:227], v19 offset:32
	s_waitcnt lgkmcnt(2)
	v_mfma_f32_32x32x16_bf16 v[34:49], v[24:27], v[50:53], v[34:49]
	s_waitcnt lgkmcnt(1)
	v_mfma_f32_32x32x16_bf16 v[66:81], v[28:31], v[20:23], 0
	v_mfma_f32_32x32x16_bf16 v[50:65], v[20:23], v[28:31], 0
	s_waitcnt lgkmcnt(0)
	v_mfma_f32_32x32x16_bf16 v[66:81], v[224:227], v[24:27], v[66:81]
	v_mfma_f32_32x32x16_bf16 v[50:65], v[24:27], v[224:227], v[50:65]

; __device__ __forceinline__ int mrow(int r, int hi) { return (r & 3) + 8 * (r >> 2) + 4 * hi; }
; template <int NV, bool WITHY> __device__ __forceinline__ void scan_chunk(const ScanLds& L, f32x16& st, bool hasT, int kt, int vt, int wave, int lane_, bf16* ypark = nullptr) {
;     ...
;     if (wave == 0) {
;         __builtin_amdgcn_s_setprio(3);
; #pragma unroll
;         for (int r = 0; r < 16; ++r) { Q[r] = 0.f; QT[r] = 0.f; }
;         mm32<4>(Q, L.Bt, 72, 0, L.Kap, 72, 0, l31, hi);
;         mm32<4>(QT, L.Kap, 72, 0, L.Bt, 72, 0, l31, hi);
; #pragma unroll
;         for (int r = 0; r < 16; ++r) { const int row = mrow(r, hi); Q[r] = row < l31 ? Q[r] : 0.f; QT[r] = l31 < row ? QT[r] : 0.f; W[r] = (row == l31 ? 1.f : 0.f) - QT[r]; }
;         nat_store(L.BQ, Q, l31, hi); nat_store(L.BQT, QT, l31, hi);
.LBB0_769:
	v_mul_u32_u24_e32 v176, 0x90, v99
	v_lshlrev_b32_e32 v211, 4, v111
	v_lshlrev_b32_e32 v174, 2, v111
	v_mul_u32_u24_e32 v169, 0x50, v99
	v_mov_b32_e32 v18, 0
	s_andn2_b64 vcc, exec, s[0:1]
	v_add3_u32 v177, s5, v176, v211
	v_or_b32_e32 v172, 1, v174
	v_or_b32_e32 v168, 3, v174
	v_or_b32_e32 v170, 2, v174
	v_add3_u32 v173, s21, v169, v1
	v_add3_u32 v175, s20, v169, v1
	v_add3_u32 v171, s34, v169, v1
	s_cbranch_vccz .Lw0skip3
	v_mov_b32_e32 v66, 0
	v_mov_b32_e32 v67, 0
	v_mov_b32_e32 v68, 0
	v_mov_b32_e32 v69, 0
	v_mov_b32_e32 v70, 0
	v_mov_b32_e32 v71, 0
	v_mov_b32_e32 v72, 0
	v_mov_b32_e32 v73, 0
	v_mov_b32_e32 v74, 0
	v_mov_b32_e32 v75, 0
	v_mov_b32_e32 v76, 0
	v_mov_b32_e32 v77, 0
	v_mov_b32_e32 v78, 0
	v_mov_b32_e32 v79, 0
	v_mov_b32_e32 v80, 0
	v_mov_b32_e32 v81, 0
	v_mov_b32_e32 v34, 0
	v_mov_b32_e32 v35, 0
	v_mov_b32_e32 v36, 0
	v_mov_b32_e32 v37, 0
	v_mov_b32_e32 v38, 0
	v_mov_b32_e32 v39, 0
	v_mov_b32_e32 v40, 0
	v_mov_b32_e32 v41, 0
	v_mov_b32_e32 v42, 0
	v_mov_b32_e32 v43, 0
	v_mov_b32_e32 v44, 0
	v_mov_b32_e32 v45, 0
	v_mov_b32_e32 v46, 0
	v_mov_b32_e32 v47, 0
	v_mov_b32_e32 v48, 0
	v_mov_b32_e32 v49, 0
	s_branch .LBB0_771
.Lw0skip3:
	s_setprio 3
	v_add3_u32 v19, s57, v176, v211
	ds_read_b128 v[20:23], v19
	ds_read_b128 v[24:27], v19 offset:32
	ds_read_b128 v[28:31], v177
	ds_read_b128 v[66:69], v177 offset:32
	ds_read_b128 v[70:73], v19 offset:64
	ds_read_b128 v[74:77], v177 offset:64
	ds_read_b128 v[78:81], v19 offset:96
	ds_read_b128 v[212:215], v177 offset:96
	v_cmp_lt_i32_e64 s[54:55], v99, v174
	s_waitcnt lgkmcnt(5)
	v_mfma_f32_32x32x16_bf16 v[50:65], v[28:31], v[20:23], 0
	v_cmp_lt_i32_e32 vcc, v174, v99
	v_add_u32_e32 v33, 24, v174
	v_add_u32_e32 v32, 25, v174
	v_mfma_f32_32x32x16_bf16 v[34:49], v[20:23], v[28:31], 0
	v_add_u32_e32 v29, 16, v174
	v_add_u32_e32 v28, 17, v174
	v_add_u32_e32 v31, 18, v174
	v_add_u32_e32 v30, 19, v174
	s_waitcnt lgkmcnt(4)
	v_mfma_f32_32x32x16_bf16 v[50:65], v[66:69], v[24:27], v[50:65]
	v_mfma_f32_32x32x16_bf16 v[34:49], v[24:27], v[66:69], v[34:49]
	v_add_u32_e32 v25, 8, v174
	v_add_u32_e32 v24, 9, v174
	v_add_u32_e32 v27, 10, v174
	v_add_u32_e32 v26, 11, v174
	v_add_u32_e32 v68, 26, v174
	s_waitcnt lgkmcnt(2)
	v_mfma_f32_32x32x16_bf16 v[50:65], v[74:77], v[70:73], v[50:65]
	v_mfma_f32_32x32x16_bf16 v[34:49], v[70:73], v[74:77], v[34:49]
	s_waitcnt lgkmcnt(0)
	v_mfma_f32_32x32x16_bf16 v[50:65], v[212:215], v[78:81], v[50:65]
	v_mfma_f32_32x32x16_bf16 v[34:49], v[78:81], v[212:215], v[34:49]
	s_nop 10
	v_cndmask_b32_e64 v66, 0, v50, s[54:55]
	v_cmp_eq_u32_e64 s[54:55], v174, v99
	v_cndmask_b32_e64 v67, v51, 0, vcc
	s_nop 0
	v_cndmask_b32_e64 v20, 0, 1.0, s[54:55]
	v_cmp_lt_i32_e64 s[54:55], v172, v99
	v_cndmask_b32_e32 v19, 0, v34, vcc
	v_cmp_eq_u32_e32 vcc, v172, v99
	v_sub_f32_e32 v34, v20, v66
	v_cndmask_b32_e64 v50, 0, v35, s[54:55]
	v_cndmask_b32_e64 v20, 0, 1.0, vcc
	v_cmp_lt_i32_e32 vcc, v170, v99
	v_sub_f32_e32 v35, v20, v67
	v_cmp_lt_i32_e64 s[54:55], v99, v168
	v_cndmask_b32_e32 v51, 0, v36, vcc
	v_cmp_lt_i32_e32 vcc, v99, v170
	v_cndmask_b32_e64 v21, 0, v53, s[54:55]
	v_cmp_eq_u32_e64 s[54:55], v168, v99
	v_cndmask_b32_e32 v20, 0, v52, vcc
	v_cmp_lt_i32_e32 vcc, v168, v99
	v_cndmask_b32_e64 v23, 0, 1.0, s[54:55]
	v_cmp_lt_i32_e64 s[54:55], v99, v24
	v_cndmask_b32_e32 v52, 0, v37, vcc
	v_cmp_eq_u32_e32 vcc, v170, v99
	v_cvt_pk_bf16_f32 v50, v19, v50
	v_cvt_pk_bf16_f32 v51, v51, v52
	v_cndmask_b32_e64 v22, 0, 1.0, vcc
	v_cmp_lt_i32_e32 vcc, v25, v99
	v_pk_add_f32 v[36:37], v[22:23], v[20:21] neg_lo:[0,1] neg_hi:[0,1]
	v_cndmask_b32_e64 v23, 0, v55, s[54:55]
	v_cndmask_b32_e32 v53, 0, v38, vcc
	v_cmp_lt_i32_e32 vcc, v99, v25
	v_cmp_eq_u32_e64 s[54:55], v24, v99
	ds_write_b64 v173, v[50:51]
	v_cndmask_b32_e32 v22, 0, v54, vcc
	v_cmp_lt_i32_e32 vcc, v24, v99
	v_add_u32_e32 v19, v175, v1
	s_nop 0
	v_cndmask_b32_e32 v54, 0, v39, vcc
	v_cmp_eq_u32_e32 vcc, v25, v99
	v_cndmask_b32_e64 v25, 0, 1.0, s[54:55]
	v_cmp_lt_i32_e64 s[54:55], v99, v26
	v_cndmask_b32_e64 v24, 0, 1.0, vcc
	v_cmp_lt_i32_e32 vcc, v27, v99
	v_pk_add_f32 v[38:39], v[24:25], v[22:23] neg_lo:[0,1] neg_hi:[0,1]
	v_cndmask_b32_e64 v25, 0, v57, s[54:55]
	v_cndmask_b32_e32 v55, 0, v40, vcc
	v_cmp_lt_i32_e32 vcc, v99, v27
	v_cmp_eq_u32_e64 s[54:55], v26, v99
	v_cvt_pk_bf16_f32 v50, v53, v54
	v_cndmask_b32_e32 v24, 0, v56, vcc
	v_cmp_lt_i32_e32 vcc, v26, v99
	s_nop 1
	v_cndmask_b32_e32 v56, 0, v41, vcc
	v_cmp_eq_u32_e32 vcc, v27, v99
	v_cndmask_b32_e64 v27, 0, 1.0, s[54:55]
	v_cmp_lt_i32_e64 s[54:55], v99, v28
	v_cndmask_b32_e64 v26, 0, 1.0, vcc
	v_cmp_lt_i32_e32 vcc, v29, v99
	v_pk_add_f32 v[40:41], v[26:27], v[24:25] neg_lo:[0,1] neg_hi:[0,1]
	v_cndmask_b32_e64 v27, 0, v59, s[54:55]
	v_cndmask_b32_e32 v57, 0, v42, vcc
	v_cmp_lt_i32_e32 vcc, v99, v29
	v_cmp_eq_u32_e64 s[54:55], v28, v99
	v_cvt_pk_bf16_f32 v51, v55, v56
	v_cndmask_b32_e32 v26, 0, v58, vcc
	v_cmp_lt_i32_e32 vcc, v28, v99
	ds_write_b64 v173, v[50:51] offset:16
	s_nop 0
	v_cndmask_b32_e32 v58, 0, v43, vcc
	v_cmp_eq_u32_e32 vcc, v29, v99
	v_cndmask_b32_e64 v29, 0, 1.0, s[54:55]
	v_cmp_lt_i32_e64 s[54:55], v99, v30
	v_cndmask_b32_e64 v28, 0, 1.0, vcc
	v_cmp_lt_i32_e32 vcc, v31, v99
	v_pk_add_f32 v[42:43], v[28:29], v[26:27] neg_lo:[0,1] neg_hi:[0,1]
	v_cndmask_b32_e64 v29, 0, v61, s[54:55]
	v_cndmask_b32_e32 v59, 0, v44, vcc
	v_cmp_lt_i32_e32 vcc, v99, v31
	v_cmp_eq_u32_e64 s[54:55], v30, v99
	v_cvt_pk_bf16_f32 v50, v57, v58
	v_cndmask_b32_e32 v28, 0, v60, vcc
	v_cmp_lt_i32_e32 vcc, v30, v99
	s_nop 1
	v_cndmask_b32_e32 v60, 0, v45, vcc
	v_cmp_eq_u32_e32 vcc, v31, v99
	v_cndmask_b32_e64 v31, 0, 1.0, s[54:55]
	v_cmp_lt_i32_e64 s[54:55], v99, v32
; template <int NV, bool WITHY> __device__ __forceinline__ void scan_chunk(const ScanLds& L, f32x16& st, bool hasT, int kt, int vt, int wave, int lane_, bf16* ypark = nullptr) {
;     ...
;         nat_store(L.BQ, Q, l31, hi); nat_store(L.BQT, QT, l31, hi);
;         {   f32x16 Qn, QTn;
; #pragma unroll
;             for (int r = 0; r < 16; ++r) { Qn[r] = 0.f; QTn[r] = 0.f; }
;             mm32<2>(Qn, L.BQT, 40, 0, L.BQ, 40, 0, l31, hi); mm32<2>(QTn, L.BQ, 40, 0, L.BQT, 40, 0, l31, hi); Q = Qn; QT = QTn; }
; #pragma unroll
;         for (int n = 1; n < 3; ++n) {
;             nat_store(L.BQ, Q, l31, hi); nat_store(L.BQT, QT, l31, hi); nat_store(L.BW, W, l31, hi);
;             f32x16 Qn, QTn;
; #pragma unroll
;             for (int r = 0; r < 16; ++r) { Qn[r] = 0.f; QTn[r] = 0.f; }
;             mm32<2>(W, L.BQ, 40, 0, L.BW, 40, 0, l31, hi); mm32<2>(Qn, L.BQT, 40, 0, L.BQ, 40, 0, l31, hi); mm32<2>(QTn, L.BQ, 40, 0, L.BQT, 40, 0, l31, hi); Q = Qn; QT = QTn; }
	v_cndmask_b32_e64 v30, 0, 1.0, vcc
	v_cmp_lt_i32_e32 vcc, v33, v99
	v_pk_add_f32 v[44:45], v[30:31], v[28:29] neg_lo:[0,1] neg_hi:[0,1]
	v_cndmask_b32_e64 v31, 0, v63, s[54:55]
	v_cndmask_b32_e32 v61, 0, v46, vcc
	v_cmp_lt_i32_e32 vcc, v99, v33
	v_cmp_eq_u32_e64 s[54:55], v32, v99
	v_add_u32_e32 v63, 27, v174
	v_cndmask_b32_e32 v30, 0, v62, vcc
	v_cmp_lt_i32_e32 vcc, v32, v99
	v_cvt_pk_bf16_f32 v51, v59, v60
	ds_write_b64 v173, v[50:51] offset:32
	v_cndmask_b32_e32 v62, 0, v47, vcc
	v_cmp_eq_u32_e32 vcc, v33, v99
	v_cndmask_b32_e64 v33, 0, 1.0, s[54:55]
	v_cvt_pk_bf16_f32 v50, v61, v62
	v_cndmask_b32_e64 v32, 0, 1.0, vcc
	v_cmp_lt_i32_e32 vcc, v68, v99
	v_pk_add_f32 v[46:47], v[32:33], v[30:31] neg_lo:[0,1] neg_hi:[0,1]
	v_cmp_lt_i32_e64 s[54:55], v99, v63
	v_cndmask_b32_e32 v69, 0, v48, vcc
	v_cmp_lt_i32_e32 vcc, v99, v68
	v_cndmask_b32_e64 v33, 0, v65, s[54:55]
	v_cmp_eq_u32_e64 s[54:55], v63, v99
	v_cndmask_b32_e32 v32, 0, v64, vcc
	v_cmp_lt_i32_e32 vcc, v63, v99
	s_nop 1
	v_cndmask_b32_e32 v64, 0, v49, vcc
	v_cvt_pk_bf16_f32 v51, v69, v64
	ds_write_b64 v173, v[50:51] offset:48
	v_cvt_pk_bf16_f32 v51, v20, v21
	v_cvt_pk_bf16_f32 v20, v22, v23
	v_cvt_pk_bf16_f32 v21, v24, v25
	ds_write_b64 v175, v[20:21] offset:16
	v_cvt_pk_bf16_f32 v20, v26, v27
	v_cvt_pk_bf16_f32 v21, v28, v29
	v_cmp_eq_u32_e32 vcc, v68, v99
	v_cvt_pk_bf16_f32 v50, v66, v67
	ds_write_b64 v175, v[20:21] offset:32
	v_cvt_pk_bf16_f32 v20, v30, v31
	v_cvt_pk_bf16_f32 v21, v32, v33
	v_cndmask_b32_e64 v49, 0, 1.0, s[54:55]
	v_cndmask_b32_e64 v48, 0, 1.0, vcc
	ds_write_b64 v175, v[50:51]
	ds_write_b64 v175, v[20:21] offset:48
	v_pk_add_f32 v[48:49], v[48:49], v[32:33] neg_lo:[0,1] neg_hi:[0,1]
	v_add_u32_e32 v32, v173, v1
	ds_read_b128 v[20:23], v19
	ds_read_b128 v[24:27], v19 offset:32
	ds_read_b128 v[28:31], v32
	ds_read_b128 v[212:215], v32 offset:32
	s_waitcnt lgkmcnt(1)
	v_mfma_f32_32x32x16_bf16 v[50:65], v[20:23], v[28:31], 0
	v_add_u32_e32 v33, v171, v1
	v_mfma_f32_32x32x16_bf16 v[66:81], v[28:31], v[20:23], 0
	s_waitcnt lgkmcnt(0)
	v_mfma_f32_32x32x16_bf16 v[50:65], v[24:27], v[212:215], v[50:65]
	v_mfma_f32_32x32x16_bf16 v[66:81], v[212:215], v[24:27], v[66:81]
	s_nop 10
	v_cvt_pk_bf16_f32 v20, v50, v51
	v_cvt_pk_bf16_f32 v21, v52, v53
	ds_write_b64 v173, v[20:21]
	v_cvt_pk_bf16_f32 v20, v54, v55
	v_cvt_pk_bf16_f32 v21, v56, v57
	ds_write_b64 v173, v[20:21] offset:16
	v_cvt_pk_bf16_f32 v20, v58, v59
	v_cvt_pk_bf16_f32 v21, v60, v61
	ds_write_b64 v173, v[20:21] offset:32
	v_cvt_pk_bf16_f32 v20, v62, v63
	v_cvt_pk_bf16_f32 v21, v64, v65
	ds_write_b64 v173, v[20:21] offset:48
	v_cvt_pk_bf16_f32 v20, v66, v67
	v_cvt_pk_bf16_f32 v21, v68, v69
	ds_write_b64 v175, v[20:21]
	v_cvt_pk_bf16_f32 v20, v70, v71
	v_cvt_pk_bf16_f32 v21, v72, v73
	ds_write_b64 v175, v[20:21] offset:16
	v_cvt_pk_bf16_f32 v20, v74, v75
	v_cvt_pk_bf16_f32 v21, v76, v77
	ds_write_b64 v175, v[20:21] offset:32
	v_cvt_pk_bf16_f32 v20, v78, v79
	v_cvt_pk_bf16_f32 v21, v80, v81
	ds_write_b64 v175, v[20:21] offset:48
	v_cvt_pk_bf16_f32 v20, v34, v35
	v_cvt_pk_bf16_f32 v21, v36, v37
	ds_write_b64 v171, v[20:21]
	v_cvt_pk_bf16_f32 v20, v38, v39
	v_cvt_pk_bf16_f32 v21, v40, v41
	ds_write_b64 v171, v[20:21] offset:16
	v_cvt_pk_bf16_f32 v20, v42, v43
	v_cvt_pk_bf16_f32 v21, v44, v45
	ds_write_b64 v171, v[20:21] offset:32
	v_cvt_pk_bf16_f32 v20, v46, v47
	v_cvt_pk_bf16_f32 v21, v48, v49
	ds_write_b64 v171, v[20:21] offset:48
	ds_read_b128 v[20:23], v32
	ds_read_b128 v[24:27], v32 offset:32
	ds_read_b128 v[28:31], v33
	ds_read_b128 v[50:53], v33 offset:32
	s_waitcnt lgkmcnt(1)
	v_mfma_f32_32x32x16_bf16 v[34:49], v[20:23], v[28:31], v[34:49]
	ds_read_b128 v[28:31], v19
	ds_read_b128 v[212:215], v19 offset:32
	s_waitcnt lgkmcnt(1)
	v_mfma_f32_32x32x16_bf16 v[66:81], v[28:31], v[20:23], 0
	v_mfma_f32_32x32x16_bf16 v[34:49], v[24:27], v[50:53], v[34:49]
	v_mfma_f32_32x32x16_bf16 v[50:65], v[20:23], v[28:31], 0
	s_waitcnt lgkmcnt(0)
	v_mfma_f32_32x32x16_bf16 v[66:81], v[212:215], v[24:27], v[66:81]
	v_mfma_f32_32x32x16_bf16 v[50:65], v[24:27], v[212:215], v[50:65]
	s_nop 10
	v_cvt_pk_bf16_f32 v20, v66, v67
	v_cvt_pk_bf16_f32 v21, v68, v69
	ds_write_b64 v173, v[20:21]
	v_cvt_pk_bf16_f32 v20, v70, v71
	v_cvt_pk_bf16_f32 v21, v72, v73
	ds_write_b64 v173, v[20:21] offset:16
	v_cvt_pk_bf16_f32 v20, v74, v75
	v_cvt_pk_bf16_f32 v21, v76, v77
	ds_write_b64 v173, v[20:21] offset:32
	v_cvt_pk_bf16_f32 v20, v78, v79
	v_cvt_pk_bf16_f32 v21, v80, v81
	ds_write_b64 v173, v[20:21] offset:48
	v_cvt_pk_bf16_f32 v20, v50, v51
	v_cvt_pk_bf16_f32 v21, v52, v53
	ds_write_b64 v175, v[20:21]
	v_cvt_pk_bf16_f32 v20, v54, v55
	v_cvt_pk_bf16_f32 v21, v56, v57
	ds_write_b64 v175, v[20:21] offset:16
	v_cvt_pk_bf16_f32 v20, v58, v59
	v_cvt_pk_bf16_f32 v21, v60, v61
	ds_write_b64 v175, v[20:21] offset:32
	v_cvt_pk_bf16_f32 v20, v62, v63
	v_cvt_pk_bf16_f32 v21, v64, v65
	ds_write_b64 v175, v[20:21] offset:48
	v_cvt_pk_bf16_f32 v20, v34, v35
	v_cvt_pk_bf16_f32 v21, v36, v37
	ds_write_b64 v171, v[20:21]
	v_cvt_pk_bf16_f32 v20, v38, v39
	v_cvt_pk_bf16_f32 v21, v40, v41
	ds_write_b64 v171, v[20:21] offset:16
	v_cvt_pk_bf16_f32 v20, v42, v43
	v_cvt_pk_bf16_f32 v21, v44, v45
	ds_write_b64 v171, v[20:21] offset:32
	v_cvt_pk_bf16_f32 v20, v46, v47
	v_cvt_pk_bf16_f32 v21, v48, v49
	ds_write_b64 v171, v[20:21] offset:48
	ds_read_b128 v[20:23], v32
	ds_read_b128 v[24:27], v32 offset:32
	ds_read_b128 v[28:31], v33
	ds_read_b128 v[50:53], v33 offset:32
	s_waitcnt lgkmcnt(1)
	v_mfma_f32_32x32x16_bf16 v[34:49], v[20:23], v[28:31], v[34:49]
	ds_read_b128 v[28:31], v19
	ds_read_b128 v[212:215], v19 offset:32
	s_waitcnt lgkmcnt(2)
	v_mfma_f32_32x32x16_bf16 v[34:49], v[24:27], v[50:53], v[34:49]
	s_waitcnt lgkmcnt(1)
	v_mfma_f32_32x32x16_bf16 v[66:81], v[28:31], v[20:23], 0
	v_mfma_f32_32x32x16_bf16 v[50:65], v[20:23], v[28:31], 0
	s_waitcnt lgkmcnt(0)
	v_mfma_f32_32x32x16_bf16 v[66:81], v[212:215], v[24:27], v[66:81]
	v_mfma_f32_32x32x16_bf16 v[50:65], v[24:27], v[212:215], v[50:65]

; template <bool COOP>
; __global__ void __launch_bounds__(NTHR, 2) fwd_kernel(Args a0) {
;     extern __shared__ __attribute__((aligned(16))) unsigned char lds_raw[];
	.amdhsa_kernel _Z10fwd_kernelILb1EEv4Args
		.amdhsa_group_segment_fixed_size 0
		.amdhsa_private_segment_fixed_size 0
		.amdhsa_kernarg_size 512
		.amdhsa_user_sgpr_count 2
		.amdhsa_user_sgpr_dispatch_ptr 0
		.amdhsa_user_sgpr_queue_ptr 0
		.amdhsa_user_sgpr_kernarg_segment_ptr 1
		.amdhsa_user_sgpr_dispatch_id 0
		.amdhsa_user_sgpr_kernarg_preload_length 0
		.amdhsa_user_sgpr_kernarg_preload_offset 0
		.amdhsa_user_sgpr_private_segment_size 0
		.amdhsa_uses_dynamic_stack 0
		.amdhsa_enable_private_segment 0
		.amdhsa_system_sgpr_workgroup_id_x 1
		.amdhsa_system_sgpr_workgroup_id_y 0
		.amdhsa_system_sgpr_workgroup_id_z 0
		.amdhsa_system_sgpr_workgroup_info 0
		.amdhsa_system_vgpr_workitem_id 2
		.amdhsa_next_free_vgpr 256
		.amdhsa_next_free_sgpr 100
		.amdhsa_accum_offset 256
		.amdhsa_reserve_vcc 1
		.amdhsa_float_round_mode_32 0
		.amdhsa_float_round_mode_16_64 0
		.amdhsa_float_denorm_mode_32 3
		.amdhsa_float_denorm_mode_16_64 3
		.amdhsa_dx10_clamp 1
		.amdhsa_ieee_mode 1
		.amdhsa_fp16_overflow 0
		.amdhsa_tg_split 0
		.amdhsa_exception_fp_ieee_invalid_op 0
		.amdhsa_exception_fp_denorm_src 0
		.amdhsa_exception_fp_ieee_div_zero 0
		.amdhsa_exception_fp_ieee_overflow 0
		.amdhsa_exception_fp_ieee_underflow 0
		.amdhsa_exception_fp_ieee_inexact 0
		.amdhsa_exception_int_div_zero 0
	.end_amdhsa_kernel

; template <bool COOP>
; __global__ void __launch_bounds__(NTHR, 2) fwd_kernel(Args a0) {
;     extern __shared__ __attribute__((aligned(16))) unsigned char lds_raw[];
amdhsa.kernels:
  - .agpr_count:     0
    .args:
      - .offset:         0
        .size:           256
        .value_kind:     by_value
      - .offset:         256
        .size:           4
        .value_kind:     hidden_block_count_x
      - .offset:         260
        .size:           4
        .value_kind:     hidden_block_count_y
      - .offset:         264
        .size:           4
        .value_kind:     hidden_block_count_z
      - .offset:         268
        .size:           2
        .value_kind:     hidden_group_size_x
      - .offset:         270
        .size:           2
        .value_kind:     hidden_group_size_y
      - .offset:         272
        .size:           2
        .value_kind:     hidden_group_size_z
      - .offset:         274
        .size:           2
        .value_kind:     hidden_remainder_x
      - .offset:         276
        .size:           2
        .value_kind:     hidden_remainder_y
      - .offset:         278
        .size:           2
        .value_kind:     hidden_remainder_z
      - .offset:         296
        .size:           8
        .value_kind:     hidden_global_offset_x
      - .offset:         304
        .size:           8
        .value_kind:     hidden_global_offset_y
      - .offset:         312
        .size:           8
        .value_kind:     hidden_global_offset_z
      - .offset:         320
        .size:           2
        .value_kind:     hidden_grid_dims
      - .offset:         344
        .size:           8
        .value_kind:     hidden_multigrid_sync_arg
      - .offset:         376
        .size:           4
        .value_kind:     hidden_dynamic_lds_size
    .group_segment_fixed_size: 0
    .kernarg_segment_align: 8
    .kernarg_segment_size: 512
    .language:       OpenCL C
    .language_version:
      - 2
      - 0
    .max_flat_workgroup_size: 512
    .name:           _Z10fwd_kernelILb1EEv4Args
    .private_segment_fixed_size: 0
    .sgpr_count:     106
    .sgpr_spill_count: 288
    .symbol:         _Z10fwd_kernelILb1EEv4Args.kd
    .uniform_work_group_size: 1
    .uses_dynamic_stack: false
    .vgpr_count:     256
    .vgpr_spill_count: 0
    .wavefront_size: 64
  - .agpr_count:     0
    .args:
      - .offset:         0
        .size:           256
        .value_kind:     by_value
      - .offset:         256
        .size:           4
        .value_kind:     hidden_block_count_x
      - .offset:         260
        .size:           4
        .value_kind:     hidden_block_count_y
      - .offset:         264
        .size:           4
        .value_kind:     hidden_block_count_z
      - .offset:         268
        .size:           2
        .value_kind:     hidden_group_size_x
      - .offset:         270
        .size:           2
        .value_kind:     hidden_group_size_y
      - .offset:         272
        .size:           2
        .value_kind:     hidden_group_size_z
      - .offset:         274
        .size:           2
        .value_kind:     hidden_remainder_x
      - .offset:         276
        .size:           2
        .value_kind:     hidden_remainder_y
      - .offset:         278
        .size:           2
        .value_kind:     hidden_remainder_z
      - .offset:         296
        .size:           8
        .value_kind:     hidden_global_offset_x
      - .offset:         304
        .size:           8
        .value_kind:     hidden_global_offset_y
      - .offset:         312
        .size:           8
        .value_kind:     hidden_global_offset_z
      - .offset:         320
        .size:           2
        .value_kind:     hidden_grid_dims
      - .offset:         376
        .size:           4
        .value_kind:     hidden_dynamic_lds_size
    .group_segment_fixed_size: 0
    .kernarg_segment_align: 8
    .kernarg_segment_size: 512
    .language:       OpenCL C
    .language_version:
      - 2
      - 0
    .max_flat_workgroup_size: 512
    .name:           _Z10fwd_kernelILb0EEv4Args
    .private_segment_fixed_size: 0
    .sgpr_count:     104
    .sgpr_spill_count: 241
    .symbol:         _Z10fwd_kernelILb0EEv4Args.kd
    .uniform_work_group_size: 1
    .uses_dynamic_stack: false
    .vgpr_count:     244
    .vgpr_spill_count: 0
    .wavefront_size: 64
